# zero-free first K-iteration: per-tile accumulator zeroing removed, a peeled first iteration uses SrcC=0 for each accumulator's first MFMA (all six loops)
# speedup vs baseline: 1.0135x; 1.0037x over previous
; #define LAS __attribute__((address_space(3)))
; __global__ void __launch_bounds__(NTHREADS, 2) fwd_megakernel(Params p) {
;     extern __shared__ __attribute__((aligned(16))) unsigned char lds_raw[];
;     LAS unsigned char* lds = (LAS unsigned char*)lds_raw;
;     const int G = gridDim.x, c = blockIdx.x;
;     volatile LAS unsigned* xst = (volatile LAS unsigned*)(lds + STAGE_BYTES);
;     unsigned* barw = (unsigned*)(p.ws + WS_BAR);
;     if (threadIdx.x < 2) xst[threadIdx.x] = 0u;
;     __syncthreads();
;     const XcdBarrier xb = xcd_barrier_post(barw, xst);
_Z14fwd_megakernel6Params:
	s_load_dwordx16 s[12:27], s[0:1], 0x40
	s_load_dword s33, s[0:1], 0x80
	s_mov_b32 s8, s2
	s_mov_b32 s101, 0
	s_mov_b32 s100, 0
	s_add_u32 s2, s0, 0x80
	s_addc_u32 s3, s1, 0
	v_cmp_gt_u32_e32 vcc, 2, v0
	v_writelane_b32 v230, s2, 0
	s_nop 1
	v_writelane_b32 v230, s3, 1
	s_and_saveexec_b64 s[2:3], vcc
	v_lshl_add_u32 v1, v0, 2, 0
	v_add_u32_e32 v1, 0x20000, v1
	v_mov_b32_e32 v2, 0
	ds_write_b32 v1, v2
	s_or_b64 exec, exec, s[2:3]
	s_load_dwordx16 s[36:51], s[0:1], 0x0
	s_waitcnt lgkmcnt(0)
	s_add_u32 s88, s26, 0x2f040000
	s_barrier
	s_getreg_b32 s0, hwreg(HW_REG_XCC_ID, 0, 4)
	s_addc_u32 s89, s27, 0
	s_and_b32 s0, s0, 15
	v_writelane_b32 v230, s0, 2
	v_cmp_eq_u32_e64 s[0:1], 0, v0
	s_mov_b64 s[2:3], exec
	s_nop 0
	v_writelane_b32 v230, s0, 3
	s_nop 1
	v_writelane_b32 v230, s1, 4
	s_and_b64 s[0:1], s[2:3], s[0:1]
	s_mov_b64 exec, s[0:1]
	s_cbranch_execz .LBB0_5
	s_mov_b64 s[4:5], exec
	v_mbcnt_lo_u32_b32 v1, s4, 0
	v_mbcnt_hi_u32_b32 v1, s5, v1
	v_cmp_eq_u32_e32 vcc, 0, v1
	s_and_b64 s[0:1], exec, vcc
	s_mov_b64 exec, s[0:1]
	s_cbranch_execz .LBB0_5
	v_readlane_b32 s0, v230, 2
	s_lshl_b32 s0, s0, 8
	s_bcnt1_i32_b64 s1, s[4:5]
	v_mov_b32_e32 v1, s0
	v_mov_b32_e32 v2, s1
	global_atomic_add v1, v2, s[88:89] offset:1024

; #define G_STAGE(bufoff, gbase, voff) do { _Pragma("unroll") for (int _i = 0; _i < 2; ++_i) \
;         __builtin_amdgcn_global_load_lds((const unsigned*)((const char*)(gbase) + (voff)[_i]), (LAS unsigned*)(lds + (bufoff) + ldsw + _i * 8192), 16, 0, 0); } while (0)
; #define G_WAIT_L(n) asm volatile("s_waitcnt lgkmcnt(" #n ")" ::: "memory")
; #define G_BAR __builtin_amdgcn_s_barrier()
; #define G_SCHED __builtin_amdgcn_sched_barrier(0)
; template <int MODE  , class Epi, class Sched>
; __device__ __forceinline__ void gemm_phase(LAS unsigned char* lds, const GemmDesc g, const Sched& S, const Epi& E) {
;     ...
;     f32x4 acc[2][2][4][2];
; #pragma unroll
;     for (int a = 0; a < 2; ++a)
; #pragma unroll
;         for (int b = 0; b < 2; ++b)
; #pragma unroll
;             for (int m = 0; m < 4; ++m)
; #pragma unroll
;                 for (int n = 0; n < 2; ++n) acc[a][b][m][n] = (f32x4){0.f, 0.f, 0.f, 0.f};
;     ...
;             G_LDB(B0, 0, 0); G_SCHED; G_LDA(At, 0, 0); G_STAGE(G_SA(1, 1), a1 + hstepA, voffA);
;             G_WAIT_L(8); G_BAR; G_WAIT_L(0); G_MMA(0, 0, At, B0); G_BAR; G_SCHED;
;             G_LDB(B1, 0, 1); G_STAGE(G_SB(0, 0), b2, voffB);
;             G_BAR; G_WAIT_L(0); G_MMA(0, 1, At, B1); G_BAR;
;             G_LDA(At, 0, 1); G_STAGE(G_SA(0, 0), a2, voffA);
;             G_BAR; G_WAIT_L(0); G_MMA(1, 0, At, B0); G_BAR; G_SCHED;
.LBB0_526:
	s_add_u32 s72, s40, 0x100
	v_mov_b32_e32 v10, 0
	s_addc_u32 s76, s41, 0
	s_mov_b32 s77, -2
	v_lshl_add_u32 v198, s73, 8, v1
	v_ashrrev_i32_e32 v199, 31, v198
	v_lshl_add_u64 v[198:199], v[198:199], 2, s[4:5]
	global_load_dword v248, v[198:199], off
	global_load_dword v249, v[198:199], off offset:64
	global_load_dword v250, v[198:199], off offset:128
	global_load_dword v251, v[198:199], off offset:192
	global_load_dword v252, v[198:199], off offset:512
	global_load_dword v253, v[198:199], off offset:576
	global_load_dword v254, v[198:199], off offset:640
	global_load_dword v255, v[198:199], off offset:704
	s_lshl_b32 s0, s75, 8
	s_add_i32 s10, s0, 0xfffffc00
	s_ashr_i32 s11, s10, 31
	v_lshl_add_u64 v[198:199], s[10:11], 2, v[156:157]
	global_load_dwordx4 v[218:221], v[198:199], off
	global_load_dwordx4 v[222:225], v[198:199], off offset:16
	global_load_dwordx4 v[226:229], v[198:199], off offset:512
	global_load_dwordx4 v[158:161], v[198:199], off offset:528
	s_mov_b32 s100, 1
	s_cmp_eq_u32 s101, 1
	s_cbranch_scc0 .Lnodb_p1c
	s_barrier
	s_mov_b32 s101, 0
.Lnodb_p1c:
	s_cmp_eq_u32 s100, 1
	s_cbranch_scc0 .LBB0_527
	s_mov_b32 s100, 0
	s_add_u32 s40, s34, 0x100
	s_addc_u32 s41, s35, 0
	s_cmp_eq_u32 s77, 12
	s_cselect_b32 s47, s21, s41
	s_cselect_b32 s46, s20, s40
	s_cselect_b32 s45, s3, s76
	s_cselect_b32 s44, s2, s72
	s_mov_b32 m0, s64
	s_add_u32 s98, s34, 0x44080
	s_addc_u32 s99, s35, 0
	ds_read_b128 v[162:165], v194
	ds_read_b128 v[166:169], v194 offset:1024
	ds_read_b128 v[170:173], v194 offset:2048
	ds_read_b128 v[174:177], v194 offset:3072
	ds_read_b128 v[178:181], v194 offset:4096
	ds_read_b128 v[182:185], v194 offset:5120
	ds_read_b128 v[186:189], v194 offset:6144
	ds_read_b128 v[198:201], v194 offset:7168
	global_load_lds_dwordx4 v146, s[98:99]
	s_mov_b32 m0, s65
	s_nop 0
	global_load_lds_dwordx4 v150, s[98:99]
	s_waitcnt lgkmcnt(8)
	s_barrier
	s_waitcnt lgkmcnt(0)
	v_mfma_i32_16x16x64_i8 v[134:137], v[232:235], v[162:165], 0
	v_mfma_i32_16x16x64_i8 v[130:133], v[240:243], v[162:165], 0
	v_mfma_i32_16x16x64_i8 v[118:121], v[232:235], v[170:173], 0
	v_mfma_i32_16x16x64_i8 v[114:117], v[240:243], v[170:173], 0
	v_mfma_i32_16x16x64_i8 v[102:105], v[232:235], v[178:181], 0
	v_mfma_i32_16x16x64_i8 v[98:101], v[240:243], v[178:181], 0
	v_mfma_i32_16x16x64_i8 v[86:89], v[232:235], v[186:189], 0
	v_mfma_i32_16x16x64_i8 v[82:85], v[240:243], v[186:189], 0
	v_mfma_i32_16x16x64_i8 v[134:137], v[236:239], v[166:169], v[134:137]
	v_mfma_i32_16x16x64_i8 v[130:133], v[244:247], v[166:169], v[130:133]
	v_mfma_i32_16x16x64_i8 v[118:121], v[236:239], v[174:177], v[118:121]
	v_mfma_i32_16x16x64_i8 v[114:117], v[244:247], v[174:177], v[114:117]
	v_mfma_i32_16x16x64_i8 v[102:105], v[236:239], v[182:185], v[102:105]
	v_mfma_i32_16x16x64_i8 v[98:101], v[244:247], v[182:185], v[98:101]
	v_mfma_i32_16x16x64_i8 v[86:89], v[236:239], v[198:201], v[86:89]
	v_mfma_i32_16x16x64_i8 v[82:85], v[244:247], v[198:201], v[82:85]
	s_barrier
	s_mov_b32 m0, s66
	ds_read_b128 v[202:205], v195
	ds_read_b128 v[206:209], v195 offset:1024
	ds_read_b128 v[210:213], v195 offset:2048
	ds_read_b128 v[214:217], v195 offset:3072
	global_load_lds_dwordx4 v148, s[44:45]
	s_mov_b32 m0, s67
	s_nop 0
	global_load_lds_dwordx4 v152, s[44:45]
	s_barrier
	s_waitcnt lgkmcnt(0)
	v_mfma_i32_16x16x64_i8 v[142:145], v[202:205], v[162:165], 0
	v_mfma_i32_16x16x64_i8 v[138:141], v[210:213], v[162:165], 0
	v_mfma_i32_16x16x64_i8 v[126:129], v[202:205], v[170:173], 0
	v_mfma_i32_16x16x64_i8 v[122:125], v[210:213], v[170:173], 0
	v_mfma_i32_16x16x64_i8 v[110:113], v[202:205], v[178:181], 0
	v_mfma_i32_16x16x64_i8 v[106:109], v[210:213], v[178:181], 0
	v_mfma_i32_16x16x64_i8 v[94:97], v[202:205], v[186:189], 0
	v_mfma_i32_16x16x64_i8 v[90:93], v[210:213], v[186:189], 0
	v_mfma_i32_16x16x64_i8 v[142:145], v[206:209], v[166:169], v[142:145]
	v_mfma_i32_16x16x64_i8 v[138:141], v[214:217], v[166:169], v[138:141]
	v_mfma_i32_16x16x64_i8 v[126:129], v[206:209], v[174:177], v[126:129]
	v_mfma_i32_16x16x64_i8 v[122:125], v[214:217], v[174:177], v[122:125]
	v_mfma_i32_16x16x64_i8 v[110:113], v[206:209], v[182:185], v[110:113]
	v_mfma_i32_16x16x64_i8 v[106:109], v[214:217], v[182:185], v[106:109]
	v_mfma_i32_16x16x64_i8 v[94:97], v[206:209], v[198:201], v[94:97]
	v_mfma_i32_16x16x64_i8 v[90:93], v[214:217], v[198:201], v[90:93]
	s_mov_b32 m0, s55
	s_barrier
	ds_read_b128 v[162:165], v194 offset:16384
	ds_read_b128 v[166:169], v194 offset:17408
	ds_read_b128 v[170:173], v194 offset:18432
	ds_read_b128 v[174:177], v194 offset:19456
	ds_read_b128 v[178:181], v194 offset:20480
	ds_read_b128 v[182:185], v194 offset:21504
	ds_read_b128 v[186:189], v194 offset:22528
	ds_read_b128 v[198:201], v194 offset:23552
	global_load_lds_dwordx4 v146, s[46:47]
	s_mov_b32 m0, s56
	s_nop 0
	global_load_lds_dwordx4 v150, s[46:47]
	s_barrier
	s_waitcnt lgkmcnt(0)
	v_mfma_i32_16x16x64_i8 v[70:73], v[232:235], v[162:165], 0
	v_mfma_i32_16x16x64_i8 v[66:69], v[240:243], v[162:165], 0
	v_mfma_i32_16x16x64_i8 v[54:57], v[232:235], v[170:173], 0
	v_mfma_i32_16x16x64_i8 v[50:53], v[240:243], v[170:173], 0
	v_mfma_i32_16x16x64_i8 v[22:25], v[232:235], v[178:181], 0
	v_mfma_i32_16x16x64_i8 v[18:21], v[240:243], v[178:181], 0
	v_mfma_i32_16x16x64_i8 v[6:9], v[232:235], v[186:189], 0
	v_mfma_i32_16x16x64_i8 v[2:5], v[240:243], v[186:189], 0
	v_mfma_i32_16x16x64_i8 v[70:73], v[236:239], v[166:169], v[70:73]
	v_mfma_i32_16x16x64_i8 v[66:69], v[244:247], v[166:169], v[66:69]
	v_mfma_i32_16x16x64_i8 v[54:57], v[236:239], v[174:177], v[54:57]
	v_mfma_i32_16x16x64_i8 v[50:53], v[244:247], v[174:177], v[50:53]
	v_mfma_i32_16x16x64_i8 v[22:25], v[236:239], v[182:185], v[22:25]
	v_mfma_i32_16x16x64_i8 v[18:21], v[244:247], v[182:185], v[18:21]
	v_mfma_i32_16x16x64_i8 v[6:9], v[236:239], v[198:201], v[6:9]
	v_mfma_i32_16x16x64_i8 v[2:5], v[244:247], v[198:201], v[2:5]
	s_barrier
; #define G_STAGE(bufoff, gbase, voff) do { _Pragma("unroll") for (int _i = 0; _i < 2; ++_i) \
;         __builtin_amdgcn_global_load_lds((const unsigned*)((const char*)(gbase) + (voff)[_i]), (LAS unsigned*)(lds + (bufoff) + ldsw + _i * 8192), 16, 0, 0); } while (0)
; #define G_WAIT_V(n) asm volatile("s_waitcnt vmcnt(" #n ")" ::: "memory")
; #define G_WAIT_L(n) asm volatile("s_waitcnt lgkmcnt(" #n ")" ::: "memory")
; #define G_BAR __builtin_amdgcn_s_barrier()
; #define G_SCHED __builtin_amdgcn_sched_barrier(0)
; template <int MODE  , class Epi, class Sched>
; __device__ __forceinline__ void gemm_phase(LAS unsigned char* lds, const GemmDesc g, const Sched& S, const Epi& E) {
;     ...
;             G_STAGE(G_SB(0, 1), b2 + hstepB, voffB);
;             G_WAIT_V(6); G_BAR; G_MMA(1, 1, At, B1); G_BAR;
;             G_LDB(B0, 1, 0); G_SCHED; G_LDA(At, 1, 0); G_STAGE(G_SA(0, 1), a2 + hstepA, voffA);
;             G_WAIT_L(8); G_BAR; G_WAIT_L(0); G_MMA(0, 0, At, B0); G_BAR; G_SCHED;
;             G_LDB(B1, 1, 1); G_STAGE(G_SB(1, 0), b3, voffB);
	s_mov_b32 m0, s68
	s_add_u32 s0, s44, 0x44000
	s_addc_u32 s1, s45, 0
	global_load_lds_dwordx4 v148, s[0:1]
	s_mov_b32 m0, s69
	s_nop 0
	global_load_lds_dwordx4 v152, s[0:1]
	s_waitcnt vmcnt(6)
	s_barrier
	v_mfma_i32_16x16x64_i8 v[30:33], v[202:205], v[178:181], 0
	v_mfma_i32_16x16x64_i8 v[26:29], v[210:213], v[178:181], 0
	v_mfma_i32_16x16x64_i8 v[14:17], v[202:205], v[186:189], 0
	v_mfma_i32_16x16x64_i8 v[10:13], v[210:213], v[186:189], 0
	v_mfma_i32_16x16x64_i8 v[34:37], v[202:205], v[162:165], 0
	v_mfma_i32_16x16x64_i8 v[38:41], v[210:213], v[162:165], 0
	v_mfma_i32_16x16x64_i8 v[42:45], v[202:205], v[170:173], 0
	v_mfma_i32_16x16x64_i8 v[46:49], v[210:213], v[170:173], 0
	v_mfma_i32_16x16x64_i8 v[30:33], v[206:209], v[182:185], v[30:33]
	v_mfma_i32_16x16x64_i8 v[26:29], v[214:217], v[182:185], v[26:29]
	v_mfma_i32_16x16x64_i8 v[14:17], v[206:209], v[198:201], v[14:17]
	v_mfma_i32_16x16x64_i8 v[10:13], v[214:217], v[198:201], v[10:13]
	v_mfma_i32_16x16x64_i8 v[34:37], v[206:209], v[166:169], v[34:37]
	v_mfma_i32_16x16x64_i8 v[38:41], v[214:217], v[166:169], v[38:41]
	v_mfma_i32_16x16x64_i8 v[42:45], v[206:209], v[174:177], v[42:45]
	v_mfma_i32_16x16x64_i8 v[46:49], v[214:217], v[174:177], v[46:49]
	s_add_i32 s10, 0, 0x18000
	v_add_u32_e32 v78, s10, v191
	s_barrier
	ds_read_b128 v[58:61], v78
	ds_read_b128 v[62:65], v78 offset:1024
	ds_read_b128 v[74:77], v78 offset:2048
	ds_read_b128 v[78:81], v78 offset:3072
	s_add_u32 s0, s46, 0x44000
	s_addc_u32 s1, s47, 0
	s_mov_b32 m0, s57
	ds_read_b128 v[162:165], v194 offset:32768
	ds_read_b128 v[166:169], v194 offset:33792
	ds_read_b128 v[170:173], v194 offset:34816
	ds_read_b128 v[174:177], v194 offset:35840
	ds_read_b128 v[178:181], v194 offset:36864
	ds_read_b128 v[182:185], v194 offset:37888
	ds_read_b128 v[186:189], v194 offset:38912
	ds_read_b128 v[198:201], v194 offset:39936
	global_load_lds_dwordx4 v146, s[0:1]
	s_mov_b32 m0, s58
	s_nop 0
	global_load_lds_dwordx4 v150, s[0:1]
	s_waitcnt lgkmcnt(8)
	s_barrier
	s_waitcnt lgkmcnt(0)
	v_mfma_i32_16x16x64_i8 v[134:137], v[58:61], v[162:165], v[134:137]
	v_mfma_i32_16x16x64_i8 v[130:133], v[74:77], v[162:165], v[130:133]
	v_mfma_i32_16x16x64_i8 v[118:121], v[58:61], v[170:173], v[118:121]
	v_mfma_i32_16x16x64_i8 v[114:117], v[74:77], v[170:173], v[114:117]
	v_mfma_i32_16x16x64_i8 v[102:105], v[58:61], v[178:181], v[102:105]
	v_mfma_i32_16x16x64_i8 v[98:101], v[74:77], v[178:181], v[98:101]
	v_mfma_i32_16x16x64_i8 v[86:89], v[58:61], v[186:189], v[86:89]
	v_mfma_i32_16x16x64_i8 v[82:85], v[74:77], v[186:189], v[82:85]
	v_mfma_i32_16x16x64_i8 v[134:137], v[62:65], v[166:169], v[134:137]
	v_mfma_i32_16x16x64_i8 v[130:133], v[78:81], v[166:169], v[130:133]
	v_mfma_i32_16x16x64_i8 v[118:121], v[62:65], v[174:177], v[118:121]
	v_mfma_i32_16x16x64_i8 v[114:117], v[78:81], v[174:177], v[114:117]
	v_mfma_i32_16x16x64_i8 v[102:105], v[62:65], v[182:185], v[102:105]
	v_mfma_i32_16x16x64_i8 v[98:101], v[78:81], v[182:185], v[98:101]
	v_mfma_i32_16x16x64_i8 v[86:89], v[62:65], v[198:201], v[86:89]
	v_mfma_i32_16x16x64_i8 v[82:85], v[78:81], v[198:201], v[82:85]
	s_barrier
	s_add_i32 s11, 0, 0x1c000
	s_add_i32 s0, s10, s54
	v_add_u32_e32 v154, s11, v191
	s_add_u32 s98, s44, 0x80
	s_addc_u32 s99, s45, 0
	s_mov_b32 m0, s0
	ds_read_b128 v[202:205], v154
	ds_read_b128 v[206:209], v154 offset:1024
	ds_read_b128 v[210:213], v154 offset:2048
	ds_read_b128 v[214:217], v154 offset:3072
	global_load_lds_dwordx4 v148, s[98:99]
	s_add_i32 m0, s0, 0x2000
	s_nop 0
	global_load_lds_dwordx4 v152, s[98:99]
	s_barrier
; #define G_STAGE(bufoff, gbase, voff) do { _Pragma("unroll") for (int _i = 0; _i < 2; ++_i) \
;         __builtin_amdgcn_global_load_lds((const unsigned*)((const char*)(gbase) + (voff)[_i]), (LAS unsigned*)(lds + (bufoff) + ldsw + _i * 8192), 16, 0, 0); } while (0)
; #define G_WAIT_V(n) asm volatile("s_waitcnt vmcnt(" #n ")" ::: "memory")
; #define G_WAIT_L(n) asm volatile("s_waitcnt lgkmcnt(" #n ")" ::: "memory")
; #define G_BAR __builtin_amdgcn_s_barrier()
; #define G_SCHED __builtin_amdgcn_sched_barrier(0)
; template <int MODE  , class Epi, class Sched>
; __device__ __forceinline__ void gemm_phase(LAS unsigned char* lds, const GemmDesc g, const Sched& S, const Epi& E) {
;     ...
;             G_LDB(B0, 0, 0); G_SCHED; G_LDA(At, 0, 0); G_STAGE(G_SA(1, 1), a1 + hstepA, voffA);
;     ...
;             G_BAR; G_WAIT_L(0); G_MMA(0, 1, At, B1); G_BAR;
;             G_LDA(At, 1, 1); G_STAGE(G_SA(1, 0), a3, voffA);
;             G_BAR; G_WAIT_L(0); G_MMA(1, 0, At, B0); G_BAR; G_SCHED;
;             G_STAGE(G_SB(1, 1), b3 + hstepB, voffB);
;             G_WAIT_V(6); G_BAR; G_MMA(1, 1, At, B1); G_BAR;
	s_waitcnt lgkmcnt(0)
	v_mfma_i32_16x16x64_i8 v[142:145], v[202:205], v[162:165], v[142:145]
	v_mfma_i32_16x16x64_i8 v[138:141], v[210:213], v[162:165], v[138:141]
	v_mfma_i32_16x16x64_i8 v[126:129], v[202:205], v[170:173], v[126:129]
	v_mfma_i32_16x16x64_i8 v[122:125], v[210:213], v[170:173], v[122:125]
	v_mfma_i32_16x16x64_i8 v[110:113], v[202:205], v[178:181], v[110:113]
	v_mfma_i32_16x16x64_i8 v[106:109], v[210:213], v[178:181], v[106:109]
	v_mfma_i32_16x16x64_i8 v[94:97], v[202:205], v[186:189], v[94:97]
	v_mfma_i32_16x16x64_i8 v[90:93], v[210:213], v[186:189], v[90:93]
	v_mfma_i32_16x16x64_i8 v[142:145], v[206:209], v[166:169], v[142:145]
	v_mfma_i32_16x16x64_i8 v[138:141], v[214:217], v[166:169], v[138:141]
	v_mfma_i32_16x16x64_i8 v[126:129], v[206:209], v[174:177], v[126:129]
	v_mfma_i32_16x16x64_i8 v[122:125], v[214:217], v[174:177], v[122:125]
	v_mfma_i32_16x16x64_i8 v[110:113], v[206:209], v[182:185], v[110:113]
	v_mfma_i32_16x16x64_i8 v[106:109], v[214:217], v[182:185], v[106:109]
	v_mfma_i32_16x16x64_i8 v[94:97], v[206:209], v[198:201], v[94:97]
	v_mfma_i32_16x16x64_i8 v[90:93], v[214:217], v[198:201], v[90:93]
	s_mov_b32 m0, s60
	s_barrier
	ds_read_b128 v[162:165], v194 offset:49152
	ds_read_b128 v[166:169], v194 offset:50176
	ds_read_b128 v[170:173], v194 offset:51200
	ds_read_b128 v[174:177], v194 offset:52224
	ds_read_b128 v[178:181], v194 offset:53248
	ds_read_b128 v[182:185], v194 offset:54272
	ds_read_b128 v[186:189], v194 offset:55296
	ds_read_b128 v[198:201], v194 offset:56320
	s_add_u32 s98, s46, 0x80
	s_addc_u32 s99, s47, 0
	global_load_lds_dwordx4 v146, s[98:99]
	s_mov_b32 m0, s61
	s_nop 0
	global_load_lds_dwordx4 v150, s[98:99]
	s_waitcnt vmcnt(10)
	s_barrier
	s_waitcnt lgkmcnt(0)
	v_mfma_i32_16x16x64_i8 v[70:73], v[58:61], v[162:165], v[70:73]
	v_mfma_i32_16x16x64_i8 v[66:69], v[74:77], v[162:165], v[66:69]
	v_mfma_i32_16x16x64_i8 v[54:57], v[58:61], v[170:173], v[54:57]
	v_mfma_i32_16x16x64_i8 v[50:53], v[74:77], v[170:173], v[50:53]
	v_mfma_i32_16x16x64_i8 v[22:25], v[58:61], v[178:181], v[22:25]
	v_mfma_i32_16x16x64_i8 v[18:21], v[74:77], v[178:181], v[18:21]
	v_mfma_i32_16x16x64_i8 v[6:9], v[58:61], v[186:189], v[6:9]
	v_mfma_i32_16x16x64_i8 v[2:5], v[74:77], v[186:189], v[2:5]
	v_mfma_i32_16x16x64_i8 v[70:73], v[62:65], v[166:169], v[70:73]
	v_mfma_i32_16x16x64_i8 v[66:69], v[78:81], v[166:169], v[66:69]
	v_mfma_i32_16x16x64_i8 v[54:57], v[62:65], v[174:177], v[54:57]
	v_mfma_i32_16x16x64_i8 v[50:53], v[78:81], v[174:177], v[50:53]
	v_mfma_i32_16x16x64_i8 v[22:25], v[62:65], v[182:185], v[22:25]
	v_mfma_i32_16x16x64_i8 v[18:21], v[78:81], v[182:185], v[18:21]
	v_mfma_i32_16x16x64_i8 v[6:9], v[62:65], v[198:201], v[6:9]
	v_mfma_i32_16x16x64_i8 v[2:5], v[78:81], v[198:201], v[2:5]
	s_barrier
	ds_read_b128 v[232:235], v193
	ds_read_b128 v[236:239], v193 offset:1024
	ds_read_b128 v[240:243], v193 offset:2048
	ds_read_b128 v[244:247], v193 offset:3072
	s_add_u32 s0, s44, 0x44080
	s_addc_u32 s1, s45, 0
	s_add_i32 s10, s11, s54
	s_mov_b32 m0, s10
	s_nop 0
	global_load_lds_dwordx4 v148, s[0:1]
	s_add_i32 m0, s10, 0x2000
	s_nop 0
	global_load_lds_dwordx4 v152, s[0:1]
	s_waitcnt vmcnt(6)
	s_barrier
	v_mfma_i32_16x16x64_i8 v[34:37], v[202:205], v[162:165], v[34:37]
	s_add_i32 s77, s77, 2
	s_add_u32 s72, s72, 0x100
	s_addc_u32 s76, s76, 0
	s_cmp_gt_u32 s77, 13
	s_mov_b64 s[34:35], s[40:41]
	v_mfma_i32_16x16x64_i8 v[78:81], v[206:209], v[166:169], v[34:37]
	v_mfma_i32_16x16x64_i8 v[34:37], v[210:213], v[162:165], v[38:41]
	v_mfma_i32_16x16x64_i8 v[74:77], v[214:217], v[166:169], v[34:37]
	v_mfma_i32_16x16x64_i8 v[34:37], v[202:205], v[170:173], v[42:45]
	v_mfma_i32_16x16x64_i8 v[62:65], v[206:209], v[174:177], v[34:37]
	v_mfma_i32_16x16x64_i8 v[34:37], v[210:213], v[170:173], v[46:49]
	v_mfma_i32_16x16x64_i8 v[30:33], v[202:205], v[178:181], v[30:33]
	v_mfma_i32_16x16x64_i8 v[26:29], v[210:213], v[178:181], v[26:29]
	v_mfma_i32_16x16x64_i8 v[14:17], v[202:205], v[186:189], v[14:17]
	v_mfma_i32_16x16x64_i8 v[10:13], v[210:213], v[186:189], v[10:13]
	v_mfma_i32_16x16x64_i8 v[58:61], v[214:217], v[174:177], v[34:37]
	v_mfma_i32_16x16x64_i8 v[30:33], v[206:209], v[182:185], v[30:33]
	v_mfma_i32_16x16x64_i8 v[26:29], v[214:217], v[182:185], v[26:29]
	v_mfma_i32_16x16x64_i8 v[14:17], v[206:209], v[198:201], v[14:17]
	v_mfma_i32_16x16x64_i8 v[10:13], v[214:217], v[198:201], v[10:13]
	s_cbranch_scc1 .Lkdone_p1c
	s_barrier
	s_branch .LBB0_527

; #define G_STAGE(bufoff, gbase, voff) do { _Pragma("unroll") for (int _i = 0; _i < 2; ++_i) \
;         __builtin_amdgcn_global_load_lds((const unsigned*)((const char*)(gbase) + (voff)[_i]), (LAS unsigned*)(lds + (bufoff) + ldsw + _i * 8192), 16, 0, 0); } while (0)
; #define G_WAIT_V(n) asm volatile("s_waitcnt vmcnt(" #n ")" ::: "memory")
; #define G_WAIT_L(n) asm volatile("s_waitcnt lgkmcnt(" #n ")" ::: "memory")
; #define G_BAR __builtin_amdgcn_s_barrier()
; #define G_SCHED __builtin_amdgcn_sched_barrier(0)
; template <int MODE  , class Epi, class Sched>
; __device__ __forceinline__ void gemm_phase(LAS unsigned char* lds, const GemmDesc g, const Sched& S, const Epi& E) {
;     ...
;     f32x4 acc[2][2][4][2];
; #pragma unroll
;     for (int a = 0; a < 2; ++a)
; #pragma unroll
;         for (int b = 0; b < 2; ++b)
; #pragma unroll
;             for (int m = 0; m < 4; ++m)
; #pragma unroll
;                 for (int n = 0; n < 2; ++n) acc[a][b][m][n] = (f32x4){0.f, 0.f, 0.f, 0.f};
;     ...
;             G_LDB(B0, 0, 0); G_SCHED; G_LDA(At, 0, 0); G_STAGE(G_SA(1, 1), a1 + hstepA, voffA);
;             G_WAIT_L(8); G_BAR; G_WAIT_L(0); G_MMA(0, 0, At, B0); G_BAR; G_SCHED;
;             G_LDB(B1, 0, 1); G_STAGE(G_SB(0, 0), b2, voffB);
;             G_BAR; G_WAIT_L(0); G_MMA(0, 1, At, B1); G_BAR;
;             G_LDA(At, 0, 1); G_STAGE(G_SA(0, 0), a2, voffA);
;             G_BAR; G_WAIT_L(0); G_MMA(1, 0, At, B0); G_BAR; G_SCHED;
;             G_STAGE(G_SB(0, 1), b2 + hstepB, voffB);
;             G_WAIT_V(6); G_BAR; G_MMA(1, 1, At, B1); G_BAR;
.LBB0_736:
	s_add_u32 s77, s46, 0x100
	v_mov_b32_e32 v18, 0
	s_addc_u32 s78, s47, 0
	s_mov_b32 s79, -2
	v_lshl_add_u32 v200, s76, 7, v167
	v_ashrrev_i32_e32 v201, 31, v200
	v_lshlrev_b64 v[200:201], 2, v[200:201]
	v_lshl_add_u64 v[202:203], s[48:49], 0, v[200:201]
	v_lshl_add_u64 v[200:201], s[16:17], 0, v[200:201]
	global_load_dwordx4 v[232:235], v[202:203], off
	global_load_dwordx4 v[236:239], v[200:201], off
	global_load_dwordx4 v[240:243], v[202:203], off offset:16
	global_load_dwordx4 v[244:247], v[200:201], off offset:16
	s_mov_b32 s100, 1
	s_cmp_eq_u32 s101, 1
	s_cbranch_scc0 .Lnodb_p1b
	s_barrier
	s_mov_b32 s101, 0
.Lnodb_p1b:
	s_cmp_eq_u32 s100, 1
	s_cbranch_scc0 .LBB0_737
	s_mov_b32 s100, 0
	ds_read_b128 v[2:5], v168
	ds_read_b128 v[6:9], v168 offset:1024
	ds_read_b128 v[10:13], v168 offset:2048
	ds_read_b128 v[14:17], v168 offset:3072
	s_add_u32 s46, s50, 0x100
	s_addc_u32 s47, s51, 0
	s_cmp_eq_u32 s79, 12
	s_cselect_b32 s55, s45, s47
	s_cselect_b32 s54, s44, s46
	s_cselect_b32 s53, s3, s78
	s_cselect_b32 s52, s2, s77
	s_add_u32 s98, s50, 0x44080
	s_addc_u32 s99, s51, 0
	s_add_i32 m0, s62, 0xc000
	ds_read_b128 v[174:177], v169
	ds_read_b128 v[178:181], v169 offset:1024
	ds_read_b128 v[182:185], v169 offset:2048
	ds_read_b128 v[186:189], v169 offset:3072
	ds_read_b128 v[192:195], v169 offset:4096
	ds_read_b128 v[196:199], v169 offset:5120
	ds_read_b128 v[200:203], v169 offset:6144
	ds_read_b128 v[204:207], v169 offset:7168
	global_load_lds_dwordx4 v152, s[98:99]
	s_add_i32 m0, s62, 0xe000
	s_nop 0
	global_load_lds_dwordx4 v148, s[98:99]
	s_waitcnt lgkmcnt(8)
	s_barrier
	s_waitcnt lgkmcnt(0)
	v_mfma_scale_f32_16x16x128_f8f6f4 v[142:145], v[2:9], v[174:181], 0, v170, v170 op_sel_hi:[0,0,0]
	v_mfma_scale_f32_16x16x128_f8f6f4 v[138:141], v[10:17], v[174:181], 0, v170, v170 op_sel_hi:[0,0,0]
	v_mfma_scale_f32_16x16x128_f8f6f4 v[126:129], v[2:9], v[182:189], 0, v170, v170 op_sel_hi:[0,0,0]
	v_mfma_scale_f32_16x16x128_f8f6f4 v[122:125], v[10:17], v[182:189], 0, v170, v170 op_sel_hi:[0,0,0]
	v_mfma_scale_f32_16x16x128_f8f6f4 v[110:113], v[2:9], v[192:199], 0, v170, v170 op_sel_hi:[0,0,0]
	v_mfma_scale_f32_16x16x128_f8f6f4 v[106:109], v[10:17], v[192:199], 0, v170, v170 op_sel_hi:[0,0,0]
	v_mfma_scale_f32_16x16x128_f8f6f4 v[94:97], v[2:9], v[200:207], 0, v170, v170 op_sel_hi:[0,0,0]
	v_mfma_scale_f32_16x16x128_f8f6f4 v[90:93], v[10:17], v[200:207], 0, v170, v170 op_sel_hi:[0,0,0]
	s_barrier
	s_add_i32 s0, s69, s60
	s_mov_b32 m0, s0
	ds_read_b128 v[208:211], v171
	ds_read_b128 v[212:215], v171 offset:1024
	ds_read_b128 v[216:219], v171 offset:2048
	ds_read_b128 v[220:223], v171 offset:3072
	global_load_lds_dwordx4 v150, s[52:53]
	s_add_i32 m0, s0, 0x2000
	s_nop 0
	global_load_lds_dwordx4 v146, s[52:53]
	s_barrier
	s_waitcnt lgkmcnt(0)
	v_mfma_scale_f32_16x16x128_f8f6f4 v[134:137], v[208:215], v[174:181], 0, v170, v170 op_sel_hi:[0,0,0]
	v_mfma_scale_f32_16x16x128_f8f6f4 v[130:133], v[216:223], v[174:181], 0, v170, v170 op_sel_hi:[0,0,0]
	v_mfma_scale_f32_16x16x128_f8f6f4 v[118:121], v[208:215], v[182:189], 0, v170, v170 op_sel_hi:[0,0,0]
	v_mfma_scale_f32_16x16x128_f8f6f4 v[114:117], v[216:223], v[182:189], 0, v170, v170 op_sel_hi:[0,0,0]
	v_mfma_scale_f32_16x16x128_f8f6f4 v[102:105], v[208:215], v[192:199], 0, v170, v170 op_sel_hi:[0,0,0]
	v_mfma_scale_f32_16x16x128_f8f6f4 v[98:101], v[216:223], v[192:199], 0, v170, v170 op_sel_hi:[0,0,0]
	v_mfma_scale_f32_16x16x128_f8f6f4 v[86:89], v[208:215], v[200:207], 0, v170, v170 op_sel_hi:[0,0,0]
	v_mfma_scale_f32_16x16x128_f8f6f4 v[82:85], v[216:223], v[200:207], 0, v170, v170 op_sel_hi:[0,0,0]
	s_mov_b32 m0, s62
	s_barrier
	ds_read_b128 v[174:177], v169 offset:16384
	ds_read_b128 v[178:181], v169 offset:17408
	ds_read_b128 v[182:185], v169 offset:18432
	ds_read_b128 v[186:189], v169 offset:19456
	ds_read_b128 v[192:195], v169 offset:20480
	ds_read_b128 v[196:199], v169 offset:21504
	ds_read_b128 v[200:203], v169 offset:22528
	ds_read_b128 v[204:207], v169 offset:23552
	global_load_lds_dwordx4 v152, s[54:55]
	s_mov_b32 m0, s63
	s_nop 0
	global_load_lds_dwordx4 v148, s[54:55]
	s_barrier
	s_waitcnt lgkmcnt(0)
	v_mfma_scale_f32_16x16x128_f8f6f4 v[78:81], v[2:9], v[174:181], 0, v170, v170 op_sel_hi:[0,0,0]
	v_mfma_scale_f32_16x16x128_f8f6f4 v[74:77], v[10:17], v[174:181], 0, v170, v170 op_sel_hi:[0,0,0]
	v_mfma_scale_f32_16x16x128_f8f6f4 v[62:65], v[2:9], v[182:189], 0, v170, v170 op_sel_hi:[0,0,0]
	v_mfma_scale_f32_16x16x128_f8f6f4 v[58:61], v[10:17], v[182:189], 0, v170, v170 op_sel_hi:[0,0,0]
	v_mfma_scale_f32_16x16x128_f8f6f4 v[46:49], v[2:9], v[192:199], 0, v170, v170 op_sel_hi:[0,0,0]
	v_mfma_scale_f32_16x16x128_f8f6f4 v[42:45], v[10:17], v[192:199], 0, v170, v170 op_sel_hi:[0,0,0]
	v_mfma_scale_f32_16x16x128_f8f6f4 v[30:33], v[2:9], v[200:207], 0, v170, v170 op_sel_hi:[0,0,0]
	v_mfma_scale_f32_16x16x128_f8f6f4 v[26:29], v[10:17], v[200:207], 0, v170, v170 op_sel_hi:[0,0,0]
	s_barrier
	s_add_u32 s0, s52, 0x44000
	s_addc_u32 s1, s53, 0
	s_add_i32 s10, s70, s60
	s_mov_b32 m0, s10
	s_nop 0
	global_load_lds_dwordx4 v150, s[0:1]
	s_add_i32 m0, s10, 0x2000
	s_nop 0
	global_load_lds_dwordx4 v146, s[0:1]
	s_waitcnt vmcnt(6)
	s_barrier
	v_mfma_scale_f32_16x16x128_f8f6f4 v[70:73], v[208:215], v[174:181], 0, v170, v170 op_sel_hi:[0,0,0]
	v_mfma_scale_f32_16x16x128_f8f6f4 v[66:69], v[216:223], v[174:181], 0, v170, v170 op_sel_hi:[0,0,0]
	v_mfma_scale_f32_16x16x128_f8f6f4 v[54:57], v[208:215], v[182:189], 0, v170, v170 op_sel_hi:[0,0,0]
	v_mfma_scale_f32_16x16x128_f8f6f4 v[50:53], v[216:223], v[182:189], 0, v170, v170 op_sel_hi:[0,0,0]
	v_mfma_scale_f32_16x16x128_f8f6f4 v[38:41], v[208:215], v[192:199], 0, v170, v170 op_sel_hi:[0,0,0]
	v_mfma_scale_f32_16x16x128_f8f6f4 v[34:37], v[216:223], v[192:199], 0, v170, v170 op_sel_hi:[0,0,0]
	v_mfma_scale_f32_16x16x128_f8f6f4 v[22:25], v[208:215], v[200:207], 0, v170, v170 op_sel_hi:[0,0,0]
	v_mfma_scale_f32_16x16x128_f8f6f4 v[18:21], v[216:223], v[200:207], 0, v170, v170 op_sel_hi:[0,0,0]
	s_add_i32 s10, 0, 0x18000
	v_add_u32_e32 v14, s10, v166
	s_barrier
; #define G_STAGE(bufoff, gbase, voff) do { _Pragma("unroll") for (int _i = 0; _i < 2; ++_i) \
;         __builtin_amdgcn_global_load_lds((const unsigned*)((const char*)(gbase) + (voff)[_i]), (LAS unsigned*)(lds + (bufoff) + ldsw + _i * 8192), 16, 0, 0); } while (0)
; #define G_WAIT_V(n) asm volatile("s_waitcnt vmcnt(" #n ")" ::: "memory")
; #define G_WAIT_L(n) asm volatile("s_waitcnt lgkmcnt(" #n ")" ::: "memory")
; #define G_BAR __builtin_amdgcn_s_barrier()
; #define G_SCHED __builtin_amdgcn_sched_barrier(0)
; template <int MODE  , class Epi, class Sched>
; __device__ __forceinline__ void gemm_phase(LAS unsigned char* lds, const GemmDesc g, const Sched& S, const Epi& E) {
;     ...
;             G_WAIT_V(6); G_BAR; G_MMA(1, 1, At, B1); G_BAR;
;             G_LDB(B0, 1, 0); G_SCHED; G_LDA(At, 1, 0); G_STAGE(G_SA(0, 1), a2 + hstepA, voffA);
;             G_WAIT_L(8); G_BAR; G_WAIT_L(0); G_MMA(0, 0, At, B0); G_BAR; G_SCHED;
;             G_LDB(B1, 1, 1); G_STAGE(G_SB(1, 0), b3, voffB);
;             G_BAR; G_WAIT_L(0); G_MMA(0, 1, At, B1); G_BAR;
;             G_LDA(At, 1, 1); G_STAGE(G_SA(1, 0), a3, voffA);
;             G_BAR; G_WAIT_L(0); G_MMA(1, 0, At, B0); G_BAR; G_SCHED;
;             G_STAGE(G_SB(1, 1), b3 + hstepB, voffB);
;             G_WAIT_V(6); G_BAR; G_MMA(1, 1, At, B1); G_BAR;
	ds_read_b128 v[2:5], v14
	ds_read_b128 v[6:9], v14 offset:1024
	ds_read_b128 v[10:13], v14 offset:2048
	ds_read_b128 v[14:17], v14 offset:3072
	s_add_u32 s0, s54, 0x44000
	s_addc_u32 s1, s55, 0
	s_mov_b32 m0, s64
	ds_read_b128 v[174:177], v169 offset:32768
	ds_read_b128 v[178:181], v169 offset:33792
	ds_read_b128 v[182:185], v169 offset:34816
	ds_read_b128 v[186:189], v169 offset:35840
	ds_read_b128 v[192:195], v169 offset:36864
	ds_read_b128 v[196:199], v169 offset:37888
	ds_read_b128 v[200:203], v169 offset:38912
	ds_read_b128 v[204:207], v169 offset:39936
	global_load_lds_dwordx4 v152, s[0:1]
	s_mov_b32 m0, s65
	s_nop 0
	global_load_lds_dwordx4 v148, s[0:1]
	s_waitcnt lgkmcnt(8)
	s_barrier
	s_waitcnt lgkmcnt(0)
	v_mfma_scale_f32_16x16x128_f8f6f4 v[142:145], v[2:9], v[174:181], v[142:145], v170, v170 op_sel_hi:[0,0,0]
	v_mfma_scale_f32_16x16x128_f8f6f4 v[138:141], v[10:17], v[174:181], v[138:141], v170, v170 op_sel_hi:[0,0,0]
	v_mfma_scale_f32_16x16x128_f8f6f4 v[126:129], v[2:9], v[182:189], v[126:129], v170, v170 op_sel_hi:[0,0,0]
	v_mfma_scale_f32_16x16x128_f8f6f4 v[122:125], v[10:17], v[182:189], v[122:125], v170, v170 op_sel_hi:[0,0,0]
	v_mfma_scale_f32_16x16x128_f8f6f4 v[110:113], v[2:9], v[192:199], v[110:113], v170, v170 op_sel_hi:[0,0,0]
	v_mfma_scale_f32_16x16x128_f8f6f4 v[106:109], v[10:17], v[192:199], v[106:109], v170, v170 op_sel_hi:[0,0,0]
	v_mfma_scale_f32_16x16x128_f8f6f4 v[94:97], v[2:9], v[200:207], v[94:97], v170, v170 op_sel_hi:[0,0,0]
	v_mfma_scale_f32_16x16x128_f8f6f4 v[90:93], v[10:17], v[200:207], v[90:93], v170, v170 op_sel_hi:[0,0,0]
	s_barrier
	s_add_i32 s11, 0, 0x1c000
	s_add_i32 s0, s10, s60
	v_add_u32_e32 v173, s11, v166
	s_add_u32 s98, s52, 0x80
	s_addc_u32 s99, s53, 0
	s_mov_b32 m0, s0
	ds_read_b128 v[208:211], v173
	ds_read_b128 v[212:215], v173 offset:1024
	ds_read_b128 v[216:219], v173 offset:2048
	ds_read_b128 v[220:223], v173 offset:3072
	global_load_lds_dwordx4 v150, s[98:99]
	s_add_i32 m0, s0, 0x2000
	s_nop 0
	global_load_lds_dwordx4 v146, s[98:99]
	s_barrier
	s_waitcnt lgkmcnt(0)
	v_mfma_scale_f32_16x16x128_f8f6f4 v[134:137], v[208:215], v[174:181], v[134:137], v170, v170 op_sel_hi:[0,0,0]
	v_mfma_scale_f32_16x16x128_f8f6f4 v[130:133], v[216:223], v[174:181], v[130:133], v170, v170 op_sel_hi:[0,0,0]
	v_mfma_scale_f32_16x16x128_f8f6f4 v[118:121], v[208:215], v[182:189], v[118:121], v170, v170 op_sel_hi:[0,0,0]
	v_mfma_scale_f32_16x16x128_f8f6f4 v[114:117], v[216:223], v[182:189], v[114:117], v170, v170 op_sel_hi:[0,0,0]
	v_mfma_scale_f32_16x16x128_f8f6f4 v[102:105], v[208:215], v[192:199], v[102:105], v170, v170 op_sel_hi:[0,0,0]
	v_mfma_scale_f32_16x16x128_f8f6f4 v[98:101], v[216:223], v[192:199], v[98:101], v170, v170 op_sel_hi:[0,0,0]
	v_mfma_scale_f32_16x16x128_f8f6f4 v[86:89], v[208:215], v[200:207], v[86:89], v170, v170 op_sel_hi:[0,0,0]
	v_mfma_scale_f32_16x16x128_f8f6f4 v[82:85], v[216:223], v[200:207], v[82:85], v170, v170 op_sel_hi:[0,0,0]
	s_mov_b32 m0, s67
	s_add_u32 s98, s54, 0x80
	s_addc_u32 s99, s55, 0
	s_barrier
	ds_read_b128 v[174:177], v169 offset:49152
	ds_read_b128 v[178:181], v169 offset:50176
	ds_read_b128 v[182:185], v169 offset:51200
	ds_read_b128 v[186:189], v169 offset:52224
	ds_read_b128 v[192:195], v169 offset:53248
	ds_read_b128 v[196:199], v169 offset:54272
	ds_read_b128 v[200:203], v169 offset:55296
	ds_read_b128 v[204:207], v169 offset:56320
	global_load_lds_dwordx4 v152, s[98:99]
	s_mov_b32 m0, s68
	s_nop 0
	global_load_lds_dwordx4 v148, s[98:99]
	s_barrier
	s_waitcnt lgkmcnt(0)
	v_mfma_scale_f32_16x16x128_f8f6f4 v[78:81], v[2:9], v[174:181], v[78:81], v170, v170 op_sel_hi:[0,0,0]
	v_mfma_scale_f32_16x16x128_f8f6f4 v[74:77], v[10:17], v[174:181], v[74:77], v170, v170 op_sel_hi:[0,0,0]
	v_mfma_scale_f32_16x16x128_f8f6f4 v[62:65], v[2:9], v[182:189], v[62:65], v170, v170 op_sel_hi:[0,0,0]
	v_mfma_scale_f32_16x16x128_f8f6f4 v[58:61], v[10:17], v[182:189], v[58:61], v170, v170 op_sel_hi:[0,0,0]
	v_mfma_scale_f32_16x16x128_f8f6f4 v[46:49], v[2:9], v[192:199], v[46:49], v170, v170 op_sel_hi:[0,0,0]
	v_mfma_scale_f32_16x16x128_f8f6f4 v[42:45], v[10:17], v[192:199], v[42:45], v170, v170 op_sel_hi:[0,0,0]
	v_mfma_scale_f32_16x16x128_f8f6f4 v[30:33], v[2:9], v[200:207], v[30:33], v170, v170 op_sel_hi:[0,0,0]
	v_mfma_scale_f32_16x16x128_f8f6f4 v[26:29], v[10:17], v[200:207], v[26:29], v170, v170 op_sel_hi:[0,0,0]
	s_barrier
	s_add_u32 s0, s52, 0x44080
	s_addc_u32 s1, s53, 0
	s_add_i32 s10, s11, s60
	s_mov_b32 m0, s10
	s_nop 0
	global_load_lds_dwordx4 v150, s[0:1]
	s_add_i32 m0, s10, 0x2000
	s_nop 0
	global_load_lds_dwordx4 v146, s[0:1]
	s_waitcnt vmcnt(6)
	s_barrier
	v_mfma_scale_f32_16x16x128_f8f6f4 v[70:73], v[208:215], v[174:181], v[70:73], v170, v170 op_sel_hi:[0,0,0]
	s_add_i32 s79, s79, 2
	s_add_u32 s77, s77, 0x100
	s_addc_u32 s78, s78, 0
	s_cmp_gt_u32 s79, 13
	s_mov_b64 s[50:51], s[46:47]
	v_mfma_scale_f32_16x16x128_f8f6f4 v[66:69], v[216:223], v[174:181], v[66:69], v170, v170 op_sel_hi:[0,0,0]
	v_mfma_scale_f32_16x16x128_f8f6f4 v[54:57], v[208:215], v[182:189], v[54:57], v170, v170 op_sel_hi:[0,0,0]
	v_mfma_scale_f32_16x16x128_f8f6f4 v[50:53], v[216:223], v[182:189], v[50:53], v170, v170 op_sel_hi:[0,0,0]
	v_mfma_scale_f32_16x16x128_f8f6f4 v[38:41], v[208:215], v[192:199], v[38:41], v170, v170 op_sel_hi:[0,0,0]
	v_mfma_scale_f32_16x16x128_f8f6f4 v[34:37], v[216:223], v[192:199], v[34:37], v170, v170 op_sel_hi:[0,0,0]
	v_mfma_scale_f32_16x16x128_f8f6f4 v[22:25], v[208:215], v[200:207], v[22:25], v170, v170 op_sel_hi:[0,0,0]
	v_mfma_scale_f32_16x16x128_f8f6f4 v[18:21], v[216:223], v[200:207], v[18:21], v170, v170 op_sel_hi:[0,0,0]
	s_cbranch_scc1 .Lkdone_p1b
	s_barrier
	s_branch .LBB0_737

; #define G_STAGE(bufoff, gbase, voff) do { _Pragma("unroll") for (int _i = 0; _i < 2; ++_i) \
;         __builtin_amdgcn_global_load_lds((const unsigned*)((const char*)(gbase) + (voff)[_i]), (LAS unsigned*)(lds + (bufoff) + ldsw + _i * 8192), 16, 0, 0); } while (0)
; #define G_WAIT_V(n) asm volatile("s_waitcnt vmcnt(" #n ")" ::: "memory")
; #define G_WAIT_L(n) asm volatile("s_waitcnt lgkmcnt(" #n ")" ::: "memory")
; #define G_BAR __builtin_amdgcn_s_barrier()
; #define G_SCHED __builtin_amdgcn_sched_barrier(0)
; template <int MODE  , class Epi, class Sched>
; __device__ __forceinline__ void gemm_phase(LAS unsigned char* lds, const GemmDesc g, const Sched& S, const Epi& E) {
;     ...
;             G_LDB(B0, 0, 0); G_SCHED; G_LDA(At, 0, 0); G_STAGE(G_SA(1, 1), a1 + hstepA, voffA);
;             G_WAIT_L(8); G_BAR; G_WAIT_L(0); G_MMA(0, 0, At, B0); G_BAR; G_SCHED;
;             G_LDB(B1, 0, 1); G_STAGE(G_SB(0, 0), b2, voffB);
;             G_BAR; G_WAIT_L(0); G_MMA(0, 1, At, B1); G_BAR;
;             G_LDA(At, 0, 1); G_STAGE(G_SA(0, 0), a2, voffA);
;             G_BAR; G_WAIT_L(0); G_MMA(1, 0, At, B0); G_BAR; G_SCHED;
;             G_STAGE(G_SB(0, 1), b2 + hstepB, voffB);
;             G_WAIT_V(6); G_BAR; G_MMA(1, 1, At, B1); G_BAR;
;     ...
;         if (zero) {
; #pragma unroll
;             for (int a = 0; a < 2; ++a)
; #pragma unroll
;                 for (int b = 0; b < 2; ++b)
; #pragma unroll
;                     for (int m = 0; m < 4; ++m)
; #pragma unroll
;                         for (int n = 0; n < 2; ++n) acc[a][b][m][n] = (f32x4){0.f, 0.f, 0.f, 0.f};
;         }
.Lnodb_sa:
	s_cmp_eq_u32 s100, 1
	s_cbranch_scc0 .LBB0_815
	s_mov_b32 s100, 0
	v_add_u32_e32 v142, s58, v172
	ds_read_b128 v[130:133], v142
	ds_read_b128 v[134:137], v142 offset:1024
	ds_read_b128 v[138:141], v142 offset:2048
	ds_read_b128 v[142:145], v142 offset:3072
	s_add_u32 s44, s42, 0x100
	s_addc_u32 s45, s43, 0
	s_cmp_eq_u32 s68, 12
	s_cselect_b32 s49, s35, s45
	s_cselect_b32 s48, s34, s44
	s_cselect_b32 s47, s3, s67
	s_cselect_b32 s46, s2, s21
	s_add_u32 s98, s42, 0x84080
	s_addc_u32 s99, s43, 0
	s_add_i32 m0, s52, 0xc000
	ds_read_b128 v[158:161], v174
	ds_read_b128 v[162:165], v174 offset:1024
	ds_read_b128 v[166:169], v174 offset:2048
	ds_read_b128 v[176:179], v174 offset:3072
	ds_read_b128 v[180:183], v174 offset:4096
	ds_read_b128 v[184:187], v174 offset:5120
	ds_read_b128 v[192:195], v174 offset:6144
	ds_read_b128 v[196:199], v174 offset:7168
	global_load_lds_dwordx4 v146, s[98:99]
	s_add_i32 m0, s52, 0xe000
	s_nop 0
	global_load_lds_dwordx4 v150, s[98:99]
	s_waitcnt lgkmcnt(8)
	s_barrier
	s_waitcnt lgkmcnt(0)
	v_mfma_f32_16x16x32_bf16 v[126:129], v[130:133], v[158:161], 0
	v_mfma_f32_16x16x32_bf16 v[122:125], v[138:141], v[158:161], 0
	v_mfma_f32_16x16x32_bf16 v[118:121], v[130:133], v[166:169], 0
	v_mfma_f32_16x16x32_bf16 v[114:117], v[138:141], v[166:169], 0
	v_mfma_f32_16x16x32_bf16 v[110:113], v[130:133], v[180:183], 0
	v_mfma_f32_16x16x32_bf16 v[106:109], v[138:141], v[180:183], 0
	v_mfma_f32_16x16x32_bf16 v[102:105], v[130:133], v[192:195], 0
	v_mfma_f32_16x16x32_bf16 v[98:101], v[138:141], v[192:195], 0
	v_mfma_f32_16x16x32_bf16 v[126:129], v[134:137], v[162:165], v[126:129]
	v_mfma_f32_16x16x32_bf16 v[122:125], v[142:145], v[162:165], v[122:125]
	v_mfma_f32_16x16x32_bf16 v[118:121], v[134:137], v[176:179], v[118:121]
	v_mfma_f32_16x16x32_bf16 v[114:117], v[142:145], v[176:179], v[114:117]
	v_mfma_f32_16x16x32_bf16 v[110:113], v[134:137], v[184:187], v[110:113]
	v_mfma_f32_16x16x32_bf16 v[106:109], v[142:145], v[184:187], v[106:109]
	v_mfma_f32_16x16x32_bf16 v[102:105], v[134:137], v[196:199], v[102:105]
	v_mfma_f32_16x16x32_bf16 v[98:101], v[142:145], v[196:199], v[98:101]
	s_barrier
	v_add_u32_e32 v170, s59, v172
	s_add_i32 s0, s58, s51
	ds_read_b128 v[200:203], v170
	ds_read_b128 v[204:207], v170 offset:1024
	ds_read_b128 v[208:211], v170 offset:2048
	ds_read_b128 v[212:215], v170 offset:3072
	s_mov_b32 m0, s0
	s_nop 0
	global_load_lds_dwordx4 v148, s[46:47]
	s_add_i32 m0, s0, 0x2000
	s_nop 0
	global_load_lds_dwordx4 v152, s[46:47]
	s_barrier
	s_waitcnt lgkmcnt(0)
	v_mfma_f32_16x16x32_bf16 v[94:97], v[200:203], v[158:161], 0
	v_mfma_f32_16x16x32_bf16 v[90:93], v[208:211], v[158:161], 0
	v_mfma_f32_16x16x32_bf16 v[86:89], v[200:203], v[166:169], 0
	v_mfma_f32_16x16x32_bf16 v[82:85], v[208:211], v[166:169], 0
	v_mfma_f32_16x16x32_bf16 v[78:81], v[200:203], v[180:183], 0
	v_mfma_f32_16x16x32_bf16 v[74:77], v[208:211], v[180:183], 0
	v_mfma_f32_16x16x32_bf16 v[70:73], v[200:203], v[192:195], 0
	v_mfma_f32_16x16x32_bf16 v[66:69], v[208:211], v[192:195], 0
	v_mfma_f32_16x16x32_bf16 v[94:97], v[204:207], v[162:165], v[94:97]
	v_mfma_f32_16x16x32_bf16 v[90:93], v[212:215], v[162:165], v[90:93]
	v_mfma_f32_16x16x32_bf16 v[86:89], v[204:207], v[176:179], v[86:89]
	v_mfma_f32_16x16x32_bf16 v[82:85], v[212:215], v[176:179], v[82:85]
	v_mfma_f32_16x16x32_bf16 v[78:81], v[204:207], v[184:187], v[78:81]
	v_mfma_f32_16x16x32_bf16 v[74:77], v[212:215], v[184:187], v[74:77]
	v_mfma_f32_16x16x32_bf16 v[70:73], v[204:207], v[196:199], v[70:73]
	v_mfma_f32_16x16x32_bf16 v[66:69], v[212:215], v[196:199], v[66:69]
	s_mov_b32 m0, s52
	s_barrier
	ds_read_b128 v[158:161], v174 offset:16384
	ds_read_b128 v[162:165], v174 offset:17408
	ds_read_b128 v[166:169], v174 offset:18432
	ds_read_b128 v[176:179], v174 offset:19456
	ds_read_b128 v[180:183], v174 offset:20480
	ds_read_b128 v[184:187], v174 offset:21504
	ds_read_b128 v[192:195], v174 offset:22528
	ds_read_b128 v[196:199], v174 offset:23552
	global_load_lds_dwordx4 v146, s[48:49]
	s_mov_b32 m0, s53
	s_nop 0
	global_load_lds_dwordx4 v150, s[48:49]
	s_barrier
	s_waitcnt lgkmcnt(0)
	v_mfma_f32_16x16x32_bf16 v[62:65], v[130:133], v[158:161], 0
	v_mfma_f32_16x16x32_bf16 v[58:61], v[138:141], v[158:161], 0
	v_mfma_f32_16x16x32_bf16 v[54:57], v[130:133], v[166:169], 0
	v_mfma_f32_16x16x32_bf16 v[50:53], v[138:141], v[166:169], 0
	v_mfma_f32_16x16x32_bf16 v[46:49], v[130:133], v[180:183], 0
	v_mfma_f32_16x16x32_bf16 v[42:45], v[138:141], v[180:183], 0
	v_mfma_f32_16x16x32_bf16 v[38:41], v[130:133], v[192:195], 0
	v_mfma_f32_16x16x32_bf16 v[34:37], v[138:141], v[192:195], 0
	v_mfma_f32_16x16x32_bf16 v[62:65], v[134:137], v[162:165], v[62:65]
	v_mfma_f32_16x16x32_bf16 v[58:61], v[142:145], v[162:165], v[58:61]
	v_mfma_f32_16x16x32_bf16 v[54:57], v[134:137], v[176:179], v[54:57]
	v_mfma_f32_16x16x32_bf16 v[50:53], v[142:145], v[176:179], v[50:53]
	v_mfma_f32_16x16x32_bf16 v[46:49], v[134:137], v[184:187], v[46:49]
	v_mfma_f32_16x16x32_bf16 v[42:45], v[142:145], v[184:187], v[42:45]
	v_mfma_f32_16x16x32_bf16 v[38:41], v[134:137], v[196:199], v[38:41]
	v_mfma_f32_16x16x32_bf16 v[34:37], v[142:145], v[196:199], v[34:37]
	s_barrier
	s_add_u32 s0, s46, 0x84000
	s_addc_u32 s1, s47, 0
	s_add_i32 s10, s59, s51
	s_mov_b32 m0, s10
	s_nop 0
	global_load_lds_dwordx4 v148, s[0:1]
	s_add_i32 m0, s10, 0x2000
	s_nop 0
	global_load_lds_dwordx4 v152, s[0:1]
	s_waitcnt vmcnt(6)
	s_barrier
; #define G_STAGE(bufoff, gbase, voff) do { _Pragma("unroll") for (int _i = 0; _i < 2; ++_i) \
;         __builtin_amdgcn_global_load_lds((const unsigned*)((const char*)(gbase) + (voff)[_i]), (LAS unsigned*)(lds + (bufoff) + ldsw + _i * 8192), 16, 0, 0); } while (0)
; #define G_WAIT_V(n) asm volatile("s_waitcnt vmcnt(" #n ")" ::: "memory")
; #define G_WAIT_L(n) asm volatile("s_waitcnt lgkmcnt(" #n ")" ::: "memory")
; #define G_BAR __builtin_amdgcn_s_barrier()
; #define G_SCHED __builtin_amdgcn_sched_barrier(0)
; template <int MODE  , class Epi, class Sched>
; __device__ __forceinline__ void gemm_phase(LAS unsigned char* lds, const GemmDesc g, const Sched& S, const Epi& E) {
;     ...
;             G_WAIT_V(6); G_BAR; G_MMA(1, 1, At, B1); G_BAR;
;             G_LDB(B0, 1, 0); G_SCHED; G_LDA(At, 1, 0); G_STAGE(G_SA(0, 1), a2 + hstepA, voffA);
;             G_WAIT_L(8); G_BAR; G_WAIT_L(0); G_MMA(0, 0, At, B0); G_BAR; G_SCHED;
;             G_LDB(B1, 1, 1); G_STAGE(G_SB(1, 0), b3, voffB);
	v_mfma_f32_16x16x32_bf16 v[30:33], v[200:203], v[158:161], 0
	v_mfma_f32_16x16x32_bf16 v[26:29], v[208:211], v[158:161], 0
	v_mfma_f32_16x16x32_bf16 v[22:25], v[200:203], v[166:169], 0
	v_mfma_f32_16x16x32_bf16 v[18:21], v[208:211], v[166:169], 0
	v_mfma_f32_16x16x32_bf16 v[14:17], v[200:203], v[180:183], 0
	v_mfma_f32_16x16x32_bf16 v[10:13], v[208:211], v[180:183], 0
	v_mfma_f32_16x16x32_bf16 v[6:9], v[200:203], v[192:195], 0
	v_mfma_f32_16x16x32_bf16 v[2:5], v[208:211], v[192:195], 0
	v_mfma_f32_16x16x32_bf16 v[30:33], v[204:207], v[162:165], v[30:33]
	v_mfma_f32_16x16x32_bf16 v[26:29], v[212:215], v[162:165], v[26:29]
	v_mfma_f32_16x16x32_bf16 v[22:25], v[204:207], v[176:179], v[22:25]
	v_mfma_f32_16x16x32_bf16 v[18:21], v[212:215], v[176:179], v[18:21]
	v_mfma_f32_16x16x32_bf16 v[14:17], v[204:207], v[184:187], v[14:17]
	v_mfma_f32_16x16x32_bf16 v[10:13], v[212:215], v[184:187], v[10:13]
	v_mfma_f32_16x16x32_bf16 v[6:9], v[204:207], v[196:199], v[6:9]
	v_mfma_f32_16x16x32_bf16 v[2:5], v[212:215], v[196:199], v[2:5]
	s_add_i32 s10, 0, 0x18000
	v_add_u32_e32 v142, s10, v172
	s_barrier
	ds_read_b128 v[130:133], v142
	ds_read_b128 v[134:137], v142 offset:1024
	ds_read_b128 v[138:141], v142 offset:2048
	ds_read_b128 v[142:145], v142 offset:3072
	s_add_u32 s0, s48, 0x84000
	s_addc_u32 s1, s49, 0
	s_mov_b32 m0, s54
	ds_read_b128 v[158:161], v174 offset:32768
	ds_read_b128 v[162:165], v174 offset:33792
	ds_read_b128 v[166:169], v174 offset:34816
	ds_read_b128 v[176:179], v174 offset:35840
	ds_read_b128 v[180:183], v174 offset:36864
	ds_read_b128 v[184:187], v174 offset:37888
	ds_read_b128 v[192:195], v174 offset:38912
	ds_read_b128 v[196:199], v174 offset:39936
	global_load_lds_dwordx4 v146, s[0:1]
	s_mov_b32 m0, s55
	s_nop 0
	global_load_lds_dwordx4 v150, s[0:1]
	s_waitcnt lgkmcnt(8)
	s_barrier
	s_waitcnt lgkmcnt(0)
	v_mfma_f32_16x16x32_bf16 v[126:129], v[130:133], v[158:161], v[126:129]
	v_mfma_f32_16x16x32_bf16 v[122:125], v[138:141], v[158:161], v[122:125]
	v_mfma_f32_16x16x32_bf16 v[118:121], v[130:133], v[166:169], v[118:121]
	v_mfma_f32_16x16x32_bf16 v[114:117], v[138:141], v[166:169], v[114:117]
	v_mfma_f32_16x16x32_bf16 v[110:113], v[130:133], v[180:183], v[110:113]
	v_mfma_f32_16x16x32_bf16 v[106:109], v[138:141], v[180:183], v[106:109]
	v_mfma_f32_16x16x32_bf16 v[102:105], v[130:133], v[192:195], v[102:105]
	v_mfma_f32_16x16x32_bf16 v[98:101], v[138:141], v[192:195], v[98:101]
	v_mfma_f32_16x16x32_bf16 v[126:129], v[134:137], v[162:165], v[126:129]
	v_mfma_f32_16x16x32_bf16 v[122:125], v[142:145], v[162:165], v[122:125]
	v_mfma_f32_16x16x32_bf16 v[118:121], v[134:137], v[176:179], v[118:121]
	v_mfma_f32_16x16x32_bf16 v[114:117], v[142:145], v[176:179], v[114:117]
	v_mfma_f32_16x16x32_bf16 v[110:113], v[134:137], v[184:187], v[110:113]
	v_mfma_f32_16x16x32_bf16 v[106:109], v[142:145], v[184:187], v[106:109]
	v_mfma_f32_16x16x32_bf16 v[102:105], v[134:137], v[196:199], v[102:105]
	v_mfma_f32_16x16x32_bf16 v[98:101], v[142:145], v[196:199], v[98:101]
	s_barrier
	s_add_i32 s11, 0, 0x1c000
	s_add_i32 s0, s10, s51
	v_add_u32_e32 v175, s11, v172
	s_add_u32 s98, s46, 0x80
	s_addc_u32 s99, s47, 0
	s_mov_b32 m0, s0
	ds_read_b128 v[200:203], v175
	ds_read_b128 v[204:207], v175 offset:1024
	ds_read_b128 v[208:211], v175 offset:2048
	ds_read_b128 v[212:215], v175 offset:3072
	global_load_lds_dwordx4 v148, s[98:99]
	s_add_i32 m0, s0, 0x2000
	s_nop 0
	global_load_lds_dwordx4 v152, s[98:99]
	s_barrier
; #define G_STAGE(bufoff, gbase, voff) do { _Pragma("unroll") for (int _i = 0; _i < 2; ++_i) \
;         __builtin_amdgcn_global_load_lds((const unsigned*)((const char*)(gbase) + (voff)[_i]), (LAS unsigned*)(lds + (bufoff) + ldsw + _i * 8192), 16, 0, 0); } while (0)
; #define G_WAIT_V(n) asm volatile("s_waitcnt vmcnt(" #n ")" ::: "memory")
; #define G_WAIT_L(n) asm volatile("s_waitcnt lgkmcnt(" #n ")" ::: "memory")
; #define G_BAR __builtin_amdgcn_s_barrier()
; #define G_SCHED __builtin_amdgcn_sched_barrier(0)
; template <int MODE  , class Epi, class Sched>
; __device__ __forceinline__ void gemm_phase(LAS unsigned char* lds, const GemmDesc g, const Sched& S, const Epi& E) {
;     ...
;             G_BAR; G_WAIT_L(0); G_MMA(0, 1, At, B1); G_BAR;
;             G_LDA(At, 1, 1); G_STAGE(G_SA(1, 0), a3, voffA);
;             G_BAR; G_WAIT_L(0); G_MMA(1, 0, At, B0); G_BAR; G_SCHED;
;             G_STAGE(G_SB(1, 1), b3 + hstepB, voffB);
;             G_WAIT_V(6); G_BAR; G_MMA(1, 1, At, B1); G_BAR;
	s_waitcnt lgkmcnt(0)
	v_mfma_f32_16x16x32_bf16 v[94:97], v[200:203], v[158:161], v[94:97]
	v_mfma_f32_16x16x32_bf16 v[90:93], v[208:211], v[158:161], v[90:93]
	v_mfma_f32_16x16x32_bf16 v[86:89], v[200:203], v[166:169], v[86:89]
	v_mfma_f32_16x16x32_bf16 v[82:85], v[208:211], v[166:169], v[82:85]
	v_mfma_f32_16x16x32_bf16 v[78:81], v[200:203], v[180:183], v[78:81]
	v_mfma_f32_16x16x32_bf16 v[74:77], v[208:211], v[180:183], v[74:77]
	v_mfma_f32_16x16x32_bf16 v[70:73], v[200:203], v[192:195], v[70:73]
	v_mfma_f32_16x16x32_bf16 v[66:69], v[208:211], v[192:195], v[66:69]
	v_mfma_f32_16x16x32_bf16 v[94:97], v[204:207], v[162:165], v[94:97]
	v_mfma_f32_16x16x32_bf16 v[90:93], v[212:215], v[162:165], v[90:93]
	v_mfma_f32_16x16x32_bf16 v[86:89], v[204:207], v[176:179], v[86:89]
	v_mfma_f32_16x16x32_bf16 v[82:85], v[212:215], v[176:179], v[82:85]
	v_mfma_f32_16x16x32_bf16 v[78:81], v[204:207], v[184:187], v[78:81]
	v_mfma_f32_16x16x32_bf16 v[74:77], v[212:215], v[184:187], v[74:77]
	v_mfma_f32_16x16x32_bf16 v[70:73], v[204:207], v[196:199], v[70:73]
	v_mfma_f32_16x16x32_bf16 v[66:69], v[212:215], v[196:199], v[66:69]
	s_mov_b32 m0, s56
	s_add_u32 s98, s48, 0x80
	s_addc_u32 s99, s49, 0
	s_barrier
	ds_read_b128 v[158:161], v174 offset:49152
	ds_read_b128 v[162:165], v174 offset:50176
	ds_read_b128 v[166:169], v174 offset:51200
	ds_read_b128 v[176:179], v174 offset:52224
	ds_read_b128 v[180:183], v174 offset:53248
	ds_read_b128 v[184:187], v174 offset:54272
	ds_read_b128 v[192:195], v174 offset:55296
	ds_read_b128 v[196:199], v174 offset:56320
	global_load_lds_dwordx4 v146, s[98:99]
	s_mov_b32 m0, s57
	s_nop 0
	global_load_lds_dwordx4 v150, s[98:99]
	s_barrier
	s_waitcnt lgkmcnt(0)
	v_mfma_f32_16x16x32_bf16 v[62:65], v[130:133], v[158:161], v[62:65]
	v_mfma_f32_16x16x32_bf16 v[58:61], v[138:141], v[158:161], v[58:61]
	v_mfma_f32_16x16x32_bf16 v[54:57], v[130:133], v[166:169], v[54:57]
	v_mfma_f32_16x16x32_bf16 v[50:53], v[138:141], v[166:169], v[50:53]
	v_mfma_f32_16x16x32_bf16 v[46:49], v[130:133], v[180:183], v[46:49]
	v_mfma_f32_16x16x32_bf16 v[42:45], v[138:141], v[180:183], v[42:45]
	v_mfma_f32_16x16x32_bf16 v[38:41], v[130:133], v[192:195], v[38:41]
	v_mfma_f32_16x16x32_bf16 v[34:37], v[138:141], v[192:195], v[34:37]
	v_mfma_f32_16x16x32_bf16 v[62:65], v[134:137], v[162:165], v[62:65]
	v_mfma_f32_16x16x32_bf16 v[58:61], v[142:145], v[162:165], v[58:61]
	v_mfma_f32_16x16x32_bf16 v[54:57], v[134:137], v[176:179], v[54:57]
	v_mfma_f32_16x16x32_bf16 v[50:53], v[142:145], v[176:179], v[50:53]
	v_mfma_f32_16x16x32_bf16 v[46:49], v[134:137], v[184:187], v[46:49]
	v_mfma_f32_16x16x32_bf16 v[42:45], v[142:145], v[184:187], v[42:45]
	v_mfma_f32_16x16x32_bf16 v[38:41], v[134:137], v[196:199], v[38:41]
	v_mfma_f32_16x16x32_bf16 v[34:37], v[142:145], v[196:199], v[34:37]
	s_barrier
	s_add_u32 s0, s46, 0x84080
	s_addc_u32 s1, s47, 0
	s_add_i32 s10, s11, s51
	s_mov_b32 m0, s10
	s_nop 0
	global_load_lds_dwordx4 v148, s[0:1]
	s_add_i32 m0, s10, 0x2000
	s_nop 0
	global_load_lds_dwordx4 v152, s[0:1]
	s_waitcnt vmcnt(6)
	s_barrier
	v_mfma_f32_16x16x32_bf16 v[30:33], v[200:203], v[158:161], v[30:33]
	s_add_i32 s68, s68, 2
	s_add_u32 s21, s21, 0x100
	s_addc_u32 s67, s67, 0
	s_cmp_gt_u32 s68, 13
	s_mov_b64 s[42:43], s[44:45]
	v_mfma_f32_16x16x32_bf16 v[26:29], v[208:211], v[158:161], v[26:29]
	v_mfma_f32_16x16x32_bf16 v[22:25], v[200:203], v[166:169], v[22:25]
	v_mfma_f32_16x16x32_bf16 v[18:21], v[208:211], v[166:169], v[18:21]
	v_mfma_f32_16x16x32_bf16 v[14:17], v[200:203], v[180:183], v[14:17]
	v_mfma_f32_16x16x32_bf16 v[10:13], v[208:211], v[180:183], v[10:13]
	v_mfma_f32_16x16x32_bf16 v[6:9], v[200:203], v[192:195], v[6:9]
	v_mfma_f32_16x16x32_bf16 v[2:5], v[208:211], v[192:195], v[2:5]
	v_mfma_f32_16x16x32_bf16 v[30:33], v[204:207], v[162:165], v[30:33]
	v_mfma_f32_16x16x32_bf16 v[26:29], v[212:215], v[162:165], v[26:29]
	v_mfma_f32_16x16x32_bf16 v[22:25], v[204:207], v[176:179], v[22:25]
	v_mfma_f32_16x16x32_bf16 v[18:21], v[212:215], v[176:179], v[18:21]
	v_mfma_f32_16x16x32_bf16 v[14:17], v[204:207], v[184:187], v[14:17]
	v_mfma_f32_16x16x32_bf16 v[10:13], v[212:215], v[184:187], v[10:13]
	v_mfma_f32_16x16x32_bf16 v[6:9], v[204:207], v[196:199], v[6:9]
	v_mfma_f32_16x16x32_bf16 v[2:5], v[212:215], v[196:199], v[2:5]
	s_cbranch_scc1 .Lkdone_sa
	s_barrier
	s_branch .LBB0_815

; template <int MODE  , class Epi, class Sched>
; __device__ __forceinline__ void gemm_phase(LAS unsigned char* lds, const GemmDesc g, const Sched& S, const Epi& E) {
;     ...
;         const bool zero = E(acc, cur, wr, wc, fr, fq);
;         if (!has_next) break;
;         if (zero) {
; #pragma unroll
;             for (int a = 0; a < 2; ++a)
; #pragma unroll
;                 for (int b = 0; b < 2; ++b)
; #pragma unroll
;                     for (int m = 0; m < 4; ++m)
; #pragma unroll
;                         for (int n = 0; n < 2; ++n) acc[a][b][m][n] = (f32x4){0.f, 0.f, 0.f, 0.f};
;         }
.LBB0_818:
	s_mov_b64 s[44:45], -1
	s_and_b64 vcc, exec, s[40:41]
	s_cbranch_vccz .LBB0_803
	s_andn2_b64 vcc, exec, s[42:43]
	s_cbranch_vccnz .LBB0_802
	s_mov_b32 s100, 1
	s_branch .LBB0_802

; #define G_STAGE(bufoff, gbase, voff) do { _Pragma("unroll") for (int _i = 0; _i < 2; ++_i) \
;         __builtin_amdgcn_global_load_lds((const unsigned*)((const char*)(gbase) + (voff)[_i]), (LAS unsigned*)(lds + (bufoff) + ldsw + _i * 8192), 16, 0, 0); } while (0)
; #define G_WAIT_V(n) asm volatile("s_waitcnt vmcnt(" #n ")" ::: "memory")
; #define G_WAIT_L(n) asm volatile("s_waitcnt lgkmcnt(" #n ")" ::: "memory")
; #define G_BAR __builtin_amdgcn_s_barrier()
; #define G_SCHED __builtin_amdgcn_sched_barrier(0)
; template <int MODE  , class Epi, class Sched>
; __device__ __forceinline__ void gemm_phase(LAS unsigned char* lds, const GemmDesc g, const Sched& S, const Epi& E) {
;     ...
;             G_LDB(B0, 0, 0); G_SCHED; G_LDA(At, 0, 0); G_STAGE(G_SA(1, 1), a1 + hstepA, voffA);
;             G_WAIT_L(8); G_BAR; G_WAIT_L(0); G_MMA(0, 0, At, B0); G_BAR; G_SCHED;
;             G_LDB(B1, 0, 1); G_STAGE(G_SB(0, 0), b2, voffB);
;             G_BAR; G_WAIT_L(0); G_MMA(0, 1, At, B1); G_BAR;
;             G_LDA(At, 0, 1); G_STAGE(G_SA(0, 0), a2, voffA);
;             G_BAR; G_WAIT_L(0); G_MMA(1, 0, At, B0); G_BAR; G_SCHED;
;             G_STAGE(G_SB(0, 1), b2 + hstepB, voffB);
;             G_WAIT_V(6); G_BAR; G_MMA(1, 1, At, B1); G_BAR;
.Lnodb_sb:
	s_cmp_eq_u32 s100, 1
	s_cbranch_scc0 .LBB0_897
	s_mov_b32 s100, 0
	v_add_u32_e32 v142, s57, v174
	ds_read_b128 v[130:133], v142
	ds_read_b128 v[134:137], v142 offset:1024
	ds_read_b128 v[138:141], v142 offset:2048
	ds_read_b128 v[142:145], v142 offset:3072
	s_add_u32 s42, s40, 0x100
	s_addc_u32 s43, s41, 0
	s_cmp_eq_u32 s71, 12
	s_cselect_b32 s47, s21, s43
	s_cselect_b32 s46, s20, s42
	s_cselect_b32 s45, s3, s70
	s_cselect_b32 s44, s2, s19
	s_add_u32 s98, s40, 0x84080
	s_addc_u32 s99, s41, 0
	s_add_i32 m0, s50, 0xc000
	ds_read_b128 v[158:161], v176
	ds_read_b128 v[162:165], v176 offset:1024
	ds_read_b128 v[166:169], v176 offset:2048
	ds_read_b128 v[170:173], v176 offset:3072
	ds_read_b128 v[178:181], v176 offset:4096
	ds_read_b128 v[182:185], v176 offset:5120
	ds_read_b128 v[186:189], v176 offset:6144
	ds_read_b128 v[192:195], v176 offset:7168
	global_load_lds_dwordx4 v146, s[98:99]
	s_add_i32 m0, s50, 0xe000
	s_nop 0
	global_load_lds_dwordx4 v150, s[98:99]
	s_waitcnt lgkmcnt(8)
	s_barrier
	s_waitcnt lgkmcnt(0)
	v_mfma_f32_16x16x32_bf16 v[126:129], v[130:133], v[158:161], 0
	v_mfma_f32_16x16x32_bf16 v[122:125], v[138:141], v[158:161], 0
	v_mfma_f32_16x16x32_bf16 v[118:121], v[130:133], v[166:169], 0
	v_mfma_f32_16x16x32_bf16 v[114:117], v[138:141], v[166:169], 0
	v_mfma_f32_16x16x32_bf16 v[110:113], v[130:133], v[178:181], 0
	v_mfma_f32_16x16x32_bf16 v[106:109], v[138:141], v[178:181], 0
	v_mfma_f32_16x16x32_bf16 v[102:105], v[130:133], v[186:189], 0
	v_mfma_f32_16x16x32_bf16 v[98:101], v[138:141], v[186:189], 0
	v_mfma_f32_16x16x32_bf16 v[126:129], v[134:137], v[162:165], v[126:129]
	v_mfma_f32_16x16x32_bf16 v[122:125], v[142:145], v[162:165], v[122:125]
	v_mfma_f32_16x16x32_bf16 v[118:121], v[134:137], v[170:173], v[118:121]
	v_mfma_f32_16x16x32_bf16 v[114:117], v[142:145], v[170:173], v[114:117]
	v_mfma_f32_16x16x32_bf16 v[110:113], v[134:137], v[182:185], v[110:113]
	v_mfma_f32_16x16x32_bf16 v[106:109], v[142:145], v[182:185], v[106:109]
	v_mfma_f32_16x16x32_bf16 v[102:105], v[134:137], v[192:195], v[102:105]
	v_mfma_f32_16x16x32_bf16 v[98:101], v[142:145], v[192:195], v[98:101]
	s_barrier
	s_add_i32 s0, s57, s49
	v_add_u32_e32 v177, s58, v174
	s_mov_b32 m0, s0
	ds_read_b128 v[196:199], v177
	ds_read_b128 v[200:203], v177 offset:1024
	ds_read_b128 v[204:207], v177 offset:2048
	ds_read_b128 v[208:211], v177 offset:3072
	global_load_lds_dwordx4 v148, s[44:45]
	s_add_i32 m0, s0, 0x2000
	s_nop 0
	global_load_lds_dwordx4 v152, s[44:45]
	s_barrier
	s_waitcnt lgkmcnt(0)
	v_mfma_f32_16x16x32_bf16 v[94:97], v[196:199], v[158:161], 0
	v_mfma_f32_16x16x32_bf16 v[90:93], v[204:207], v[158:161], 0
	v_mfma_f32_16x16x32_bf16 v[86:89], v[196:199], v[166:169], 0
	v_mfma_f32_16x16x32_bf16 v[82:85], v[204:207], v[166:169], 0
	v_mfma_f32_16x16x32_bf16 v[78:81], v[196:199], v[178:181], 0
	v_mfma_f32_16x16x32_bf16 v[74:77], v[204:207], v[178:181], 0
	v_mfma_f32_16x16x32_bf16 v[70:73], v[196:199], v[186:189], 0
	v_mfma_f32_16x16x32_bf16 v[66:69], v[204:207], v[186:189], 0
	v_mfma_f32_16x16x32_bf16 v[94:97], v[200:203], v[162:165], v[94:97]
	v_mfma_f32_16x16x32_bf16 v[90:93], v[208:211], v[162:165], v[90:93]
	v_mfma_f32_16x16x32_bf16 v[86:89], v[200:203], v[170:173], v[86:89]
	v_mfma_f32_16x16x32_bf16 v[82:85], v[208:211], v[170:173], v[82:85]
	v_mfma_f32_16x16x32_bf16 v[78:81], v[200:203], v[182:185], v[78:81]
	v_mfma_f32_16x16x32_bf16 v[74:77], v[208:211], v[182:185], v[74:77]
	v_mfma_f32_16x16x32_bf16 v[70:73], v[200:203], v[192:195], v[70:73]
	v_mfma_f32_16x16x32_bf16 v[66:69], v[208:211], v[192:195], v[66:69]
	s_mov_b32 m0, s50
	s_barrier
	ds_read_b128 v[158:161], v176 offset:16384
	ds_read_b128 v[162:165], v176 offset:17408
	ds_read_b128 v[166:169], v176 offset:18432
	ds_read_b128 v[170:173], v176 offset:19456
	ds_read_b128 v[178:181], v176 offset:20480
	ds_read_b128 v[182:185], v176 offset:21504
	ds_read_b128 v[186:189], v176 offset:22528
	ds_read_b128 v[192:195], v176 offset:23552
	global_load_lds_dwordx4 v146, s[46:47]
	s_mov_b32 m0, s51
	s_nop 0
	global_load_lds_dwordx4 v150, s[46:47]
	s_barrier
	s_waitcnt lgkmcnt(0)
	v_mfma_f32_16x16x32_bf16 v[62:65], v[130:133], v[158:161], 0
	v_mfma_f32_16x16x32_bf16 v[58:61], v[138:141], v[158:161], 0
	v_mfma_f32_16x16x32_bf16 v[54:57], v[130:133], v[166:169], 0
	v_mfma_f32_16x16x32_bf16 v[50:53], v[138:141], v[166:169], 0
	v_mfma_f32_16x16x32_bf16 v[46:49], v[130:133], v[178:181], 0
	v_mfma_f32_16x16x32_bf16 v[42:45], v[138:141], v[178:181], 0
	v_mfma_f32_16x16x32_bf16 v[38:41], v[130:133], v[186:189], 0
	v_mfma_f32_16x16x32_bf16 v[34:37], v[138:141], v[186:189], 0
	v_mfma_f32_16x16x32_bf16 v[62:65], v[134:137], v[162:165], v[62:65]
	v_mfma_f32_16x16x32_bf16 v[58:61], v[142:145], v[162:165], v[58:61]
	v_mfma_f32_16x16x32_bf16 v[54:57], v[134:137], v[170:173], v[54:57]
	v_mfma_f32_16x16x32_bf16 v[50:53], v[142:145], v[170:173], v[50:53]
	v_mfma_f32_16x16x32_bf16 v[46:49], v[134:137], v[182:185], v[46:49]
	v_mfma_f32_16x16x32_bf16 v[42:45], v[142:145], v[182:185], v[42:45]
	v_mfma_f32_16x16x32_bf16 v[38:41], v[134:137], v[192:195], v[38:41]
	v_mfma_f32_16x16x32_bf16 v[34:37], v[142:145], v[192:195], v[34:37]
	s_barrier
	s_add_u32 s0, s44, 0x84000
	s_addc_u32 s1, s45, 0
	s_add_i32 s10, s58, s49
	s_mov_b32 m0, s10
	s_nop 0
	global_load_lds_dwordx4 v148, s[0:1]
	s_add_i32 m0, s10, 0x2000
	s_nop 0
	global_load_lds_dwordx4 v152, s[0:1]
	s_waitcnt vmcnt(6)
	s_barrier
; #define G_STAGE(bufoff, gbase, voff) do { _Pragma("unroll") for (int _i = 0; _i < 2; ++_i) \
;         __builtin_amdgcn_global_load_lds((const unsigned*)((const char*)(gbase) + (voff)[_i]), (LAS unsigned*)(lds + (bufoff) + ldsw + _i * 8192), 16, 0, 0); } while (0)
; #define G_WAIT_V(n) asm volatile("s_waitcnt vmcnt(" #n ")" ::: "memory")
; #define G_WAIT_L(n) asm volatile("s_waitcnt lgkmcnt(" #n ")" ::: "memory")
; #define G_BAR __builtin_amdgcn_s_barrier()
; #define G_SCHED __builtin_amdgcn_sched_barrier(0)
; template <int MODE  , class Epi, class Sched>
; __device__ __forceinline__ void gemm_phase(LAS unsigned char* lds, const GemmDesc g, const Sched& S, const Epi& E) {
;     ...
;             G_WAIT_V(6); G_BAR; G_MMA(1, 1, At, B1); G_BAR;
;             G_LDB(B0, 1, 0); G_SCHED; G_LDA(At, 1, 0); G_STAGE(G_SA(0, 1), a2 + hstepA, voffA);
;             G_WAIT_L(8); G_BAR; G_WAIT_L(0); G_MMA(0, 0, At, B0); G_BAR; G_SCHED;
;             G_LDB(B1, 1, 1); G_STAGE(G_SB(1, 0), b3, voffB);
	v_mfma_f32_16x16x32_bf16 v[30:33], v[196:199], v[158:161], 0
	v_mfma_f32_16x16x32_bf16 v[26:29], v[204:207], v[158:161], 0
	v_mfma_f32_16x16x32_bf16 v[22:25], v[196:199], v[166:169], 0
	v_mfma_f32_16x16x32_bf16 v[18:21], v[204:207], v[166:169], 0
	v_mfma_f32_16x16x32_bf16 v[14:17], v[196:199], v[178:181], 0
	v_mfma_f32_16x16x32_bf16 v[10:13], v[204:207], v[178:181], 0
	v_mfma_f32_16x16x32_bf16 v[6:9], v[196:199], v[186:189], 0
	v_mfma_f32_16x16x32_bf16 v[2:5], v[204:207], v[186:189], 0
	v_mfma_f32_16x16x32_bf16 v[30:33], v[200:203], v[162:165], v[30:33]
	v_mfma_f32_16x16x32_bf16 v[26:29], v[208:211], v[162:165], v[26:29]
	v_mfma_f32_16x16x32_bf16 v[22:25], v[200:203], v[170:173], v[22:25]
	v_mfma_f32_16x16x32_bf16 v[18:21], v[208:211], v[170:173], v[18:21]
	v_mfma_f32_16x16x32_bf16 v[14:17], v[200:203], v[182:185], v[14:17]
	v_mfma_f32_16x16x32_bf16 v[10:13], v[208:211], v[182:185], v[10:13]
	v_mfma_f32_16x16x32_bf16 v[6:9], v[200:203], v[192:195], v[6:9]
	v_mfma_f32_16x16x32_bf16 v[2:5], v[208:211], v[192:195], v[2:5]
	s_add_i32 s10, 0, 0x18000
	v_add_u32_e32 v142, s10, v174
	s_barrier
	ds_read_b128 v[130:133], v142
	ds_read_b128 v[134:137], v142 offset:1024
	ds_read_b128 v[138:141], v142 offset:2048
	ds_read_b128 v[142:145], v142 offset:3072
	s_add_u32 s0, s46, 0x84000
	s_addc_u32 s1, s47, 0
	s_mov_b32 m0, s52
	ds_read_b128 v[158:161], v176 offset:32768
	ds_read_b128 v[162:165], v176 offset:33792
	ds_read_b128 v[166:169], v176 offset:34816
	ds_read_b128 v[170:173], v176 offset:35840
	ds_read_b128 v[178:181], v176 offset:36864
	ds_read_b128 v[182:185], v176 offset:37888
	ds_read_b128 v[186:189], v176 offset:38912
	ds_read_b128 v[192:195], v176 offset:39936
	global_load_lds_dwordx4 v146, s[0:1]
	s_mov_b32 m0, s53
	s_nop 0
	global_load_lds_dwordx4 v150, s[0:1]
	s_waitcnt lgkmcnt(8)
	s_barrier
	s_waitcnt lgkmcnt(0)
	v_mfma_f32_16x16x32_bf16 v[126:129], v[130:133], v[158:161], v[126:129]
	v_mfma_f32_16x16x32_bf16 v[122:125], v[138:141], v[158:161], v[122:125]
	v_mfma_f32_16x16x32_bf16 v[118:121], v[130:133], v[166:169], v[118:121]
	v_mfma_f32_16x16x32_bf16 v[114:117], v[138:141], v[166:169], v[114:117]
	v_mfma_f32_16x16x32_bf16 v[110:113], v[130:133], v[178:181], v[110:113]
	v_mfma_f32_16x16x32_bf16 v[106:109], v[138:141], v[178:181], v[106:109]
	v_mfma_f32_16x16x32_bf16 v[102:105], v[130:133], v[186:189], v[102:105]
	v_mfma_f32_16x16x32_bf16 v[98:101], v[138:141], v[186:189], v[98:101]
	v_mfma_f32_16x16x32_bf16 v[126:129], v[134:137], v[162:165], v[126:129]
	v_mfma_f32_16x16x32_bf16 v[122:125], v[142:145], v[162:165], v[122:125]
	v_mfma_f32_16x16x32_bf16 v[118:121], v[134:137], v[170:173], v[118:121]
	v_mfma_f32_16x16x32_bf16 v[114:117], v[142:145], v[170:173], v[114:117]
	v_mfma_f32_16x16x32_bf16 v[110:113], v[134:137], v[182:185], v[110:113]
	v_mfma_f32_16x16x32_bf16 v[106:109], v[142:145], v[182:185], v[106:109]
	v_mfma_f32_16x16x32_bf16 v[102:105], v[134:137], v[192:195], v[102:105]
	v_mfma_f32_16x16x32_bf16 v[98:101], v[142:145], v[192:195], v[98:101]
	s_barrier
	s_add_i32 s11, 0, 0x1c000
	s_add_i32 s0, s10, s49
	v_add_u32_e32 v177, s11, v174
	s_add_u32 s98, s44, 0x80
	s_addc_u32 s99, s45, 0
	s_mov_b32 m0, s0
	ds_read_b128 v[196:199], v177
	ds_read_b128 v[200:203], v177 offset:1024
	ds_read_b128 v[204:207], v177 offset:2048
	ds_read_b128 v[208:211], v177 offset:3072
	global_load_lds_dwordx4 v148, s[98:99]
	s_add_i32 m0, s0, 0x2000
	s_nop 0
	global_load_lds_dwordx4 v152, s[98:99]
	s_barrier
; #define G_STAGE(bufoff, gbase, voff) do { _Pragma("unroll") for (int _i = 0; _i < 2; ++_i) \
;         __builtin_amdgcn_global_load_lds((const unsigned*)((const char*)(gbase) + (voff)[_i]), (LAS unsigned*)(lds + (bufoff) + ldsw + _i * 8192), 16, 0, 0); } while (0)
; #define G_WAIT_V(n) asm volatile("s_waitcnt vmcnt(" #n ")" ::: "memory")
; #define G_WAIT_L(n) asm volatile("s_waitcnt lgkmcnt(" #n ")" ::: "memory")
; #define G_BAR __builtin_amdgcn_s_barrier()
; #define G_SCHED __builtin_amdgcn_sched_barrier(0)
; template <int MODE  , class Epi, class Sched>
; __device__ __forceinline__ void gemm_phase(LAS unsigned char* lds, const GemmDesc g, const Sched& S, const Epi& E) {
;     ...
;             G_BAR; G_WAIT_L(0); G_MMA(0, 1, At, B1); G_BAR;
;             G_LDA(At, 1, 1); G_STAGE(G_SA(1, 0), a3, voffA);
;             G_BAR; G_WAIT_L(0); G_MMA(1, 0, At, B0); G_BAR; G_SCHED;
;             G_STAGE(G_SB(1, 1), b3 + hstepB, voffB);
;             G_WAIT_V(6); G_BAR; G_MMA(1, 1, At, B1); G_BAR;
	s_waitcnt lgkmcnt(0)
	v_mfma_f32_16x16x32_bf16 v[94:97], v[196:199], v[158:161], v[94:97]
	v_mfma_f32_16x16x32_bf16 v[90:93], v[204:207], v[158:161], v[90:93]
	v_mfma_f32_16x16x32_bf16 v[86:89], v[196:199], v[166:169], v[86:89]
	v_mfma_f32_16x16x32_bf16 v[82:85], v[204:207], v[166:169], v[82:85]
	v_mfma_f32_16x16x32_bf16 v[78:81], v[196:199], v[178:181], v[78:81]
	v_mfma_f32_16x16x32_bf16 v[74:77], v[204:207], v[178:181], v[74:77]
	v_mfma_f32_16x16x32_bf16 v[70:73], v[196:199], v[186:189], v[70:73]
	v_mfma_f32_16x16x32_bf16 v[66:69], v[204:207], v[186:189], v[66:69]
	v_mfma_f32_16x16x32_bf16 v[94:97], v[200:203], v[162:165], v[94:97]
	v_mfma_f32_16x16x32_bf16 v[90:93], v[208:211], v[162:165], v[90:93]
	v_mfma_f32_16x16x32_bf16 v[86:89], v[200:203], v[170:173], v[86:89]
	v_mfma_f32_16x16x32_bf16 v[82:85], v[208:211], v[170:173], v[82:85]
	v_mfma_f32_16x16x32_bf16 v[78:81], v[200:203], v[182:185], v[78:81]
	v_mfma_f32_16x16x32_bf16 v[74:77], v[208:211], v[182:185], v[74:77]
	v_mfma_f32_16x16x32_bf16 v[70:73], v[200:203], v[192:195], v[70:73]
	v_mfma_f32_16x16x32_bf16 v[66:69], v[208:211], v[192:195], v[66:69]
	s_mov_b32 m0, s54
	s_add_u32 s98, s46, 0x80
	s_addc_u32 s99, s47, 0
	s_barrier
	ds_read_b128 v[158:161], v176 offset:49152
	ds_read_b128 v[162:165], v176 offset:50176
	ds_read_b128 v[166:169], v176 offset:51200
	ds_read_b128 v[170:173], v176 offset:52224
	ds_read_b128 v[178:181], v176 offset:53248
	ds_read_b128 v[182:185], v176 offset:54272
	ds_read_b128 v[186:189], v176 offset:55296
	ds_read_b128 v[192:195], v176 offset:56320
	global_load_lds_dwordx4 v146, s[98:99]
	s_mov_b32 m0, s55
	s_nop 0
	global_load_lds_dwordx4 v150, s[98:99]
	s_barrier
	s_waitcnt lgkmcnt(0)
	v_mfma_f32_16x16x32_bf16 v[62:65], v[130:133], v[158:161], v[62:65]
	v_mfma_f32_16x16x32_bf16 v[58:61], v[138:141], v[158:161], v[58:61]
	v_mfma_f32_16x16x32_bf16 v[54:57], v[130:133], v[166:169], v[54:57]
	v_mfma_f32_16x16x32_bf16 v[50:53], v[138:141], v[166:169], v[50:53]
	v_mfma_f32_16x16x32_bf16 v[46:49], v[130:133], v[178:181], v[46:49]
	v_mfma_f32_16x16x32_bf16 v[42:45], v[138:141], v[178:181], v[42:45]
	v_mfma_f32_16x16x32_bf16 v[38:41], v[130:133], v[186:189], v[38:41]
	v_mfma_f32_16x16x32_bf16 v[34:37], v[138:141], v[186:189], v[34:37]
	v_mfma_f32_16x16x32_bf16 v[62:65], v[134:137], v[162:165], v[62:65]
	v_mfma_f32_16x16x32_bf16 v[58:61], v[142:145], v[162:165], v[58:61]
	v_mfma_f32_16x16x32_bf16 v[54:57], v[134:137], v[170:173], v[54:57]
	v_mfma_f32_16x16x32_bf16 v[50:53], v[142:145], v[170:173], v[50:53]
	v_mfma_f32_16x16x32_bf16 v[46:49], v[134:137], v[182:185], v[46:49]
	v_mfma_f32_16x16x32_bf16 v[42:45], v[142:145], v[182:185], v[42:45]
	v_mfma_f32_16x16x32_bf16 v[38:41], v[134:137], v[192:195], v[38:41]
	v_mfma_f32_16x16x32_bf16 v[34:37], v[142:145], v[192:195], v[34:37]
	s_barrier
	s_add_u32 s0, s44, 0x84080
	s_addc_u32 s1, s45, 0
	s_add_i32 s10, s11, s49
	s_mov_b32 m0, s10
	s_nop 0
	global_load_lds_dwordx4 v148, s[0:1]
	s_add_i32 m0, s10, 0x2000
	s_nop 0
	global_load_lds_dwordx4 v152, s[0:1]
	s_waitcnt vmcnt(6)
	s_barrier
	v_mfma_f32_16x16x32_bf16 v[30:33], v[196:199], v[158:161], v[30:33]
	s_add_i32 s71, s71, 2
	s_add_u32 s19, s19, 0x100
	s_addc_u32 s70, s70, 0
	s_cmp_gt_u32 s71, 13
	s_mov_b64 s[40:41], s[42:43]
	v_mfma_f32_16x16x32_bf16 v[26:29], v[204:207], v[158:161], v[26:29]
	v_mfma_f32_16x16x32_bf16 v[22:25], v[196:199], v[166:169], v[22:25]
	v_mfma_f32_16x16x32_bf16 v[18:21], v[204:207], v[166:169], v[18:21]
	v_mfma_f32_16x16x32_bf16 v[14:17], v[196:199], v[178:181], v[14:17]
	v_mfma_f32_16x16x32_bf16 v[10:13], v[204:207], v[178:181], v[10:13]
	v_mfma_f32_16x16x32_bf16 v[6:9], v[196:199], v[186:189], v[6:9]
	v_mfma_f32_16x16x32_bf16 v[2:5], v[204:207], v[186:189], v[2:5]
	v_mfma_f32_16x16x32_bf16 v[30:33], v[200:203], v[162:165], v[30:33]
	v_mfma_f32_16x16x32_bf16 v[26:29], v[208:211], v[162:165], v[26:29]
	v_mfma_f32_16x16x32_bf16 v[22:25], v[200:203], v[170:173], v[22:25]
	v_mfma_f32_16x16x32_bf16 v[18:21], v[208:211], v[170:173], v[18:21]
	v_mfma_f32_16x16x32_bf16 v[14:17], v[200:203], v[182:185], v[14:17]
	v_mfma_f32_16x16x32_bf16 v[10:13], v[208:211], v[182:185], v[10:13]
	v_mfma_f32_16x16x32_bf16 v[6:9], v[200:203], v[192:195], v[6:9]
	v_mfma_f32_16x16x32_bf16 v[2:5], v[208:211], v[192:195], v[2:5]
	s_cbranch_scc1 .Lkdone_sb
	s_barrier
	s_branch .LBB0_897

; template <int MODE  , class Epi, class Sched>
; __device__ __forceinline__ void gemm_phase(LAS unsigned char* lds, const GemmDesc g, const Sched& S, const Epi& E) {
;     ...
;         const bool zero = E(acc, cur, wr, wc, fr, fq);
;         if (!has_next) break;
;         if (zero) {
; #pragma unroll
;             for (int a = 0; a < 2; ++a)
; #pragma unroll
;                 for (int b = 0; b < 2; ++b)
; #pragma unroll
;                     for (int m = 0; m < 4; ++m)
; #pragma unroll
;                         for (int n = 0; n < 2; ++n) acc[a][b][m][n] = (f32x4){0.f, 0.f, 0.f, 0.f};
;         }
.LBB0_909:
	s_andn2_b64 vcc, exec, s[42:43]
	s_cbranch_vccnz .LBB0_884
	s_mov_b32 s100, 1
	s_branch .LBB0_884

; #define G_STAGE(bufoff, gbase, voff) do { _Pragma("unroll") for (int _i = 0; _i < 2; ++_i) \
;         __builtin_amdgcn_global_load_lds((const unsigned*)((const char*)(gbase) + (voff)[_i]), (LAS unsigned*)(lds + (bufoff) + ldsw + _i * 8192), 16, 0, 0); } while (0)
; #define G_WAIT_V(n) asm volatile("s_waitcnt vmcnt(" #n ")" ::: "memory")
; #define G_WAIT_L(n) asm volatile("s_waitcnt lgkmcnt(" #n ")" ::: "memory")
; #define G_BAR __builtin_amdgcn_s_barrier()
; #define G_SCHED __builtin_amdgcn_sched_barrier(0)
; template <int MODE  , class Epi, class Sched>
; __device__ __forceinline__ void gemm_phase(LAS unsigned char* lds, const GemmDesc g, const Sched& S, const Epi& E) {
;     ...
;             G_LDB(B0, 0, 0); G_SCHED; G_LDA(At, 0, 0); G_STAGE(G_SA(1, 1), a1 + hstepA, voffA);
;             G_WAIT_L(8); G_BAR; G_WAIT_L(0); G_MMA(0, 0, At, B0); G_BAR; G_SCHED;
;             G_LDB(B1, 0, 1); G_STAGE(G_SB(0, 0), b2, voffB);
;             G_BAR; G_WAIT_L(0); G_MMA(0, 1, At, B1); G_BAR;
;             G_LDA(At, 0, 1); G_STAGE(G_SA(0, 0), a2, voffA);
;             G_BAR; G_WAIT_L(0); G_MMA(1, 0, At, B0); G_BAR; G_SCHED;
;             G_STAGE(G_SB(0, 1), b2 + hstepB, voffB);
;             G_WAIT_V(6); G_BAR; G_MMA(1, 1, At, B1); G_BAR;
.Lnodb_sc:
	s_cmp_eq_u32 s100, 1
	s_cbranch_scc0 .LBB0_987
	s_mov_b32 s100, 0
	v_add_u32_e32 v145, s50, v142
	ds_read_b128 v[146:149], v145
	ds_read_b128 v[150:153], v145 offset:1024
	ds_read_b128 v[154:157], v145 offset:2048
	ds_read_b128 v[158:161], v145 offset:3072
	s_add_u32 s34, s20, 0x100
	s_addc_u32 s35, s21, 0
	s_cmp_eq_u32 s60, 12
	s_cselect_b32 s43, s17, s35
	s_cselect_b32 s42, s16, s34
	s_cselect_b32 s41, s3, s59
	s_cselect_b32 s40, s2, s15
	s_add_u32 s98, s20, 0x84080
	s_addc_u32 s99, s21, 0
	s_add_i32 m0, s44, 0xc000
	ds_read_b128 v[162:165], v144
	ds_read_b128 v[166:169], v144 offset:1024
	ds_read_b128 v[170:173], v144 offset:2048
	ds_read_b128 v[174:177], v144 offset:3072
	ds_read_b128 v[178:181], v144 offset:4096
	ds_read_b128 v[182:185], v144 offset:5120
	ds_read_b128 v[186:189], v144 offset:6144
	ds_read_b128 v[192:195], v144 offset:7168
	global_load_lds_dwordx4 v130, s[98:99]
	s_add_i32 m0, s44, 0xe000
	s_nop 0
	global_load_lds_dwordx4 v134, s[98:99]
	s_waitcnt lgkmcnt(8)
	s_barrier
	s_waitcnt lgkmcnt(0)
	v_mfma_f32_16x16x32_bf16 v[126:129], v[146:149], v[162:165], 0
	v_mfma_f32_16x16x32_bf16 v[122:125], v[154:157], v[162:165], 0
	v_mfma_f32_16x16x32_bf16 v[118:121], v[146:149], v[170:173], 0
	v_mfma_f32_16x16x32_bf16 v[114:117], v[154:157], v[170:173], 0
	v_mfma_f32_16x16x32_bf16 v[110:113], v[146:149], v[178:181], 0
	v_mfma_f32_16x16x32_bf16 v[106:109], v[154:157], v[178:181], 0
	v_mfma_f32_16x16x32_bf16 v[102:105], v[146:149], v[186:189], 0
	v_mfma_f32_16x16x32_bf16 v[98:101], v[154:157], v[186:189], 0
	v_mfma_f32_16x16x32_bf16 v[126:129], v[150:153], v[166:169], v[126:129]
	v_mfma_f32_16x16x32_bf16 v[122:125], v[158:161], v[166:169], v[122:125]
	v_mfma_f32_16x16x32_bf16 v[118:121], v[150:153], v[174:177], v[118:121]
	v_mfma_f32_16x16x32_bf16 v[114:117], v[158:161], v[174:177], v[114:117]
	v_mfma_f32_16x16x32_bf16 v[110:113], v[150:153], v[182:185], v[110:113]
	v_mfma_f32_16x16x32_bf16 v[106:109], v[158:161], v[182:185], v[106:109]
	v_mfma_f32_16x16x32_bf16 v[102:105], v[150:153], v[192:195], v[102:105]
	v_mfma_f32_16x16x32_bf16 v[98:101], v[158:161], v[192:195], v[98:101]
	s_barrier
	s_add_i32 s0, s50, s31
	v_add_u32_e32 v145, s51, v142
	s_mov_b32 m0, s0
	ds_read_b128 v[196:199], v145
	ds_read_b128 v[200:203], v145 offset:1024
	ds_read_b128 v[204:207], v145 offset:2048
	ds_read_b128 v[208:211], v145 offset:3072
	global_load_lds_dwordx4 v132, s[40:41]
	s_add_i32 m0, s0, 0x2000
	s_nop 0
	global_load_lds_dwordx4 v136, s[40:41]
	s_barrier
	s_waitcnt lgkmcnt(0)
	v_mfma_f32_16x16x32_bf16 v[94:97], v[196:199], v[162:165], 0
	v_mfma_f32_16x16x32_bf16 v[90:93], v[204:207], v[162:165], 0
	v_mfma_f32_16x16x32_bf16 v[86:89], v[196:199], v[170:173], 0
	v_mfma_f32_16x16x32_bf16 v[82:85], v[204:207], v[170:173], 0
	v_mfma_f32_16x16x32_bf16 v[78:81], v[196:199], v[178:181], 0
	v_mfma_f32_16x16x32_bf16 v[74:77], v[204:207], v[178:181], 0
	v_mfma_f32_16x16x32_bf16 v[70:73], v[196:199], v[186:189], 0
	v_mfma_f32_16x16x32_bf16 v[66:69], v[204:207], v[186:189], 0
	v_mfma_f32_16x16x32_bf16 v[94:97], v[200:203], v[166:169], v[94:97]
	v_mfma_f32_16x16x32_bf16 v[90:93], v[208:211], v[166:169], v[90:93]
	v_mfma_f32_16x16x32_bf16 v[86:89], v[200:203], v[174:177], v[86:89]
	v_mfma_f32_16x16x32_bf16 v[82:85], v[208:211], v[174:177], v[82:85]
	v_mfma_f32_16x16x32_bf16 v[78:81], v[200:203], v[182:185], v[78:81]
	v_mfma_f32_16x16x32_bf16 v[74:77], v[208:211], v[182:185], v[74:77]
	v_mfma_f32_16x16x32_bf16 v[70:73], v[200:203], v[192:195], v[70:73]
	v_mfma_f32_16x16x32_bf16 v[66:69], v[208:211], v[192:195], v[66:69]
	s_mov_b32 m0, s44
	s_barrier
	ds_read_b128 v[162:165], v144 offset:16384
	ds_read_b128 v[166:169], v144 offset:17408
	ds_read_b128 v[170:173], v144 offset:18432
	ds_read_b128 v[174:177], v144 offset:19456
	ds_read_b128 v[178:181], v144 offset:20480
	ds_read_b128 v[182:185], v144 offset:21504
	ds_read_b128 v[186:189], v144 offset:22528
	ds_read_b128 v[192:195], v144 offset:23552
	global_load_lds_dwordx4 v130, s[42:43]
	s_mov_b32 m0, s45
	s_nop 0
	global_load_lds_dwordx4 v134, s[42:43]
	s_barrier
	s_waitcnt lgkmcnt(0)
	v_mfma_f32_16x16x32_bf16 v[62:65], v[146:149], v[162:165], 0
	v_mfma_f32_16x16x32_bf16 v[58:61], v[154:157], v[162:165], 0
	v_mfma_f32_16x16x32_bf16 v[54:57], v[146:149], v[170:173], 0
	v_mfma_f32_16x16x32_bf16 v[50:53], v[154:157], v[170:173], 0
	v_mfma_f32_16x16x32_bf16 v[46:49], v[146:149], v[178:181], 0
	v_mfma_f32_16x16x32_bf16 v[42:45], v[154:157], v[178:181], 0
	v_mfma_f32_16x16x32_bf16 v[38:41], v[146:149], v[186:189], 0
	v_mfma_f32_16x16x32_bf16 v[34:37], v[154:157], v[186:189], 0
	v_mfma_f32_16x16x32_bf16 v[62:65], v[150:153], v[166:169], v[62:65]
	v_mfma_f32_16x16x32_bf16 v[58:61], v[158:161], v[166:169], v[58:61]
	v_mfma_f32_16x16x32_bf16 v[54:57], v[150:153], v[174:177], v[54:57]
	v_mfma_f32_16x16x32_bf16 v[50:53], v[158:161], v[174:177], v[50:53]
	v_mfma_f32_16x16x32_bf16 v[46:49], v[150:153], v[182:185], v[46:49]
	v_mfma_f32_16x16x32_bf16 v[42:45], v[158:161], v[182:185], v[42:45]
	v_mfma_f32_16x16x32_bf16 v[38:41], v[150:153], v[192:195], v[38:41]
	v_mfma_f32_16x16x32_bf16 v[34:37], v[158:161], v[192:195], v[34:37]
	s_barrier
	s_add_u32 s0, s40, 0x84000
	s_addc_u32 s1, s41, 0
	s_add_i32 s10, s51, s31
	s_mov_b32 m0, s10
	s_nop 0
	global_load_lds_dwordx4 v132, s[0:1]
	s_add_i32 m0, s10, 0x2000
	s_nop 0
	global_load_lds_dwordx4 v136, s[0:1]
	s_waitcnt vmcnt(6)
	s_barrier
; #define G_STAGE(bufoff, gbase, voff) do { _Pragma("unroll") for (int _i = 0; _i < 2; ++_i) \
;         __builtin_amdgcn_global_load_lds((const unsigned*)((const char*)(gbase) + (voff)[_i]), (LAS unsigned*)(lds + (bufoff) + ldsw + _i * 8192), 16, 0, 0); } while (0)
; #define G_WAIT_V(n) asm volatile("s_waitcnt vmcnt(" #n ")" ::: "memory")
; #define G_WAIT_L(n) asm volatile("s_waitcnt lgkmcnt(" #n ")" ::: "memory")
; #define G_BAR __builtin_amdgcn_s_barrier()
; #define G_SCHED __builtin_amdgcn_sched_barrier(0)
; template <int MODE  , class Epi, class Sched>
; __device__ __forceinline__ void gemm_phase(LAS unsigned char* lds, const GemmDesc g, const Sched& S, const Epi& E) {
;     ...
;             G_WAIT_V(6); G_BAR; G_MMA(1, 1, At, B1); G_BAR;
;             G_LDB(B0, 1, 0); G_SCHED; G_LDA(At, 1, 0); G_STAGE(G_SA(0, 1), a2 + hstepA, voffA);
;             G_WAIT_L(8); G_BAR; G_WAIT_L(0); G_MMA(0, 0, At, B0); G_BAR; G_SCHED;
;             G_LDB(B1, 1, 1); G_STAGE(G_SB(1, 0), b3, voffB);
	v_mfma_f32_16x16x32_bf16 v[30:33], v[196:199], v[162:165], 0
	v_mfma_f32_16x16x32_bf16 v[26:29], v[204:207], v[162:165], 0
	v_mfma_f32_16x16x32_bf16 v[22:25], v[196:199], v[170:173], 0
	v_mfma_f32_16x16x32_bf16 v[18:21], v[204:207], v[170:173], 0
	v_mfma_f32_16x16x32_bf16 v[14:17], v[196:199], v[178:181], 0
	v_mfma_f32_16x16x32_bf16 v[10:13], v[204:207], v[178:181], 0
	v_mfma_f32_16x16x32_bf16 v[6:9], v[196:199], v[186:189], 0
	v_mfma_f32_16x16x32_bf16 v[2:5], v[204:207], v[186:189], 0
	v_mfma_f32_16x16x32_bf16 v[30:33], v[200:203], v[166:169], v[30:33]
	v_mfma_f32_16x16x32_bf16 v[26:29], v[208:211], v[166:169], v[26:29]
	v_mfma_f32_16x16x32_bf16 v[22:25], v[200:203], v[174:177], v[22:25]
	v_mfma_f32_16x16x32_bf16 v[18:21], v[208:211], v[174:177], v[18:21]
	v_mfma_f32_16x16x32_bf16 v[14:17], v[200:203], v[182:185], v[14:17]
	v_mfma_f32_16x16x32_bf16 v[10:13], v[208:211], v[182:185], v[10:13]
	v_mfma_f32_16x16x32_bf16 v[6:9], v[200:203], v[192:195], v[6:9]
	v_mfma_f32_16x16x32_bf16 v[2:5], v[208:211], v[192:195], v[2:5]
	s_add_i32 s10, 0, 0x18000
	v_add_u32_e32 v145, s10, v142
	s_barrier
	ds_read_b128 v[146:149], v145
	ds_read_b128 v[150:153], v145 offset:1024
	ds_read_b128 v[154:157], v145 offset:2048
	ds_read_b128 v[158:161], v145 offset:3072
	s_add_u32 s0, s42, 0x84000
	s_addc_u32 s1, s43, 0
	s_mov_b32 m0, s46
	ds_read_b128 v[162:165], v144 offset:32768
	ds_read_b128 v[166:169], v144 offset:33792
	ds_read_b128 v[170:173], v144 offset:34816
	ds_read_b128 v[174:177], v144 offset:35840
	ds_read_b128 v[178:181], v144 offset:36864
	ds_read_b128 v[182:185], v144 offset:37888
	ds_read_b128 v[186:189], v144 offset:38912
	ds_read_b128 v[192:195], v144 offset:39936
	global_load_lds_dwordx4 v130, s[0:1]
	s_mov_b32 m0, s47
	s_nop 0
	global_load_lds_dwordx4 v134, s[0:1]
	s_waitcnt lgkmcnt(8)
	s_barrier
	s_waitcnt lgkmcnt(0)
	v_mfma_f32_16x16x32_bf16 v[126:129], v[146:149], v[162:165], v[126:129]
	v_mfma_f32_16x16x32_bf16 v[122:125], v[154:157], v[162:165], v[122:125]
	v_mfma_f32_16x16x32_bf16 v[118:121], v[146:149], v[170:173], v[118:121]
	v_mfma_f32_16x16x32_bf16 v[114:117], v[154:157], v[170:173], v[114:117]
	v_mfma_f32_16x16x32_bf16 v[110:113], v[146:149], v[178:181], v[110:113]
	v_mfma_f32_16x16x32_bf16 v[106:109], v[154:157], v[178:181], v[106:109]
	v_mfma_f32_16x16x32_bf16 v[102:105], v[146:149], v[186:189], v[102:105]
	v_mfma_f32_16x16x32_bf16 v[98:101], v[154:157], v[186:189], v[98:101]
	v_mfma_f32_16x16x32_bf16 v[126:129], v[150:153], v[166:169], v[126:129]
	v_mfma_f32_16x16x32_bf16 v[122:125], v[158:161], v[166:169], v[122:125]
	v_mfma_f32_16x16x32_bf16 v[118:121], v[150:153], v[174:177], v[118:121]
	v_mfma_f32_16x16x32_bf16 v[114:117], v[158:161], v[174:177], v[114:117]
	v_mfma_f32_16x16x32_bf16 v[110:113], v[150:153], v[182:185], v[110:113]
	v_mfma_f32_16x16x32_bf16 v[106:109], v[158:161], v[182:185], v[106:109]
	v_mfma_f32_16x16x32_bf16 v[102:105], v[150:153], v[192:195], v[102:105]
	v_mfma_f32_16x16x32_bf16 v[98:101], v[158:161], v[192:195], v[98:101]
	s_barrier
	s_add_i32 s11, 0, 0x1c000
	s_add_i32 s0, s10, s31
	v_add_u32_e32 v145, s11, v142
	s_add_u32 s98, s40, 0x80
	s_addc_u32 s99, s41, 0
	s_mov_b32 m0, s0
	ds_read_b128 v[196:199], v145
	ds_read_b128 v[200:203], v145 offset:1024
	ds_read_b128 v[204:207], v145 offset:2048
	ds_read_b128 v[208:211], v145 offset:3072
	global_load_lds_dwordx4 v132, s[98:99]
	s_add_i32 m0, s0, 0x2000
	s_nop 0
	global_load_lds_dwordx4 v136, s[98:99]
	s_barrier
; #define G_STAGE(bufoff, gbase, voff) do { _Pragma("unroll") for (int _i = 0; _i < 2; ++_i) \
;         __builtin_amdgcn_global_load_lds((const unsigned*)((const char*)(gbase) + (voff)[_i]), (LAS unsigned*)(lds + (bufoff) + ldsw + _i * 8192), 16, 0, 0); } while (0)
; #define G_WAIT_V(n) asm volatile("s_waitcnt vmcnt(" #n ")" ::: "memory")
; #define G_WAIT_L(n) asm volatile("s_waitcnt lgkmcnt(" #n ")" ::: "memory")
; #define G_BAR __builtin_amdgcn_s_barrier()
; #define G_SCHED __builtin_amdgcn_sched_barrier(0)
; template <int MODE  , class Epi, class Sched>
; __device__ __forceinline__ void gemm_phase(LAS unsigned char* lds, const GemmDesc g, const Sched& S, const Epi& E) {
;     ...
;             G_BAR; G_WAIT_L(0); G_MMA(0, 1, At, B1); G_BAR;
;             G_LDA(At, 1, 1); G_STAGE(G_SA(1, 0), a3, voffA);
;             G_BAR; G_WAIT_L(0); G_MMA(1, 0, At, B0); G_BAR; G_SCHED;
;             G_STAGE(G_SB(1, 1), b3 + hstepB, voffB);
;             G_WAIT_V(6); G_BAR; G_MMA(1, 1, At, B1); G_BAR;
	s_waitcnt lgkmcnt(0)
	v_mfma_f32_16x16x32_bf16 v[94:97], v[196:199], v[162:165], v[94:97]
	v_mfma_f32_16x16x32_bf16 v[90:93], v[204:207], v[162:165], v[90:93]
	v_mfma_f32_16x16x32_bf16 v[86:89], v[196:199], v[170:173], v[86:89]
	v_mfma_f32_16x16x32_bf16 v[82:85], v[204:207], v[170:173], v[82:85]
	v_mfma_f32_16x16x32_bf16 v[78:81], v[196:199], v[178:181], v[78:81]
	v_mfma_f32_16x16x32_bf16 v[74:77], v[204:207], v[178:181], v[74:77]
	v_mfma_f32_16x16x32_bf16 v[70:73], v[196:199], v[186:189], v[70:73]
	v_mfma_f32_16x16x32_bf16 v[66:69], v[204:207], v[186:189], v[66:69]
	v_mfma_f32_16x16x32_bf16 v[94:97], v[200:203], v[166:169], v[94:97]
	v_mfma_f32_16x16x32_bf16 v[90:93], v[208:211], v[166:169], v[90:93]
	v_mfma_f32_16x16x32_bf16 v[86:89], v[200:203], v[174:177], v[86:89]
	v_mfma_f32_16x16x32_bf16 v[82:85], v[208:211], v[174:177], v[82:85]
	v_mfma_f32_16x16x32_bf16 v[78:81], v[200:203], v[182:185], v[78:81]
	v_mfma_f32_16x16x32_bf16 v[74:77], v[208:211], v[182:185], v[74:77]
	v_mfma_f32_16x16x32_bf16 v[70:73], v[200:203], v[192:195], v[70:73]
	v_mfma_f32_16x16x32_bf16 v[66:69], v[208:211], v[192:195], v[66:69]
	s_mov_b32 m0, s48
	s_add_u32 s98, s42, 0x80
	s_addc_u32 s99, s43, 0
	s_barrier
	ds_read_b128 v[162:165], v144 offset:49152
	ds_read_b128 v[166:169], v144 offset:50176
	ds_read_b128 v[170:173], v144 offset:51200
	ds_read_b128 v[174:177], v144 offset:52224
	ds_read_b128 v[178:181], v144 offset:53248
	ds_read_b128 v[182:185], v144 offset:54272
	ds_read_b128 v[186:189], v144 offset:55296
	ds_read_b128 v[192:195], v144 offset:56320
	global_load_lds_dwordx4 v130, s[98:99]
	s_mov_b32 m0, s49
	s_nop 0
	global_load_lds_dwordx4 v134, s[98:99]
	s_barrier
	s_waitcnt lgkmcnt(0)
	v_mfma_f32_16x16x32_bf16 v[62:65], v[146:149], v[162:165], v[62:65]
	v_mfma_f32_16x16x32_bf16 v[58:61], v[154:157], v[162:165], v[58:61]
	v_mfma_f32_16x16x32_bf16 v[54:57], v[146:149], v[170:173], v[54:57]
	v_mfma_f32_16x16x32_bf16 v[50:53], v[154:157], v[170:173], v[50:53]
	v_mfma_f32_16x16x32_bf16 v[46:49], v[146:149], v[178:181], v[46:49]
	v_mfma_f32_16x16x32_bf16 v[42:45], v[154:157], v[178:181], v[42:45]
	v_mfma_f32_16x16x32_bf16 v[38:41], v[146:149], v[186:189], v[38:41]
	v_mfma_f32_16x16x32_bf16 v[34:37], v[154:157], v[186:189], v[34:37]
	v_mfma_f32_16x16x32_bf16 v[62:65], v[150:153], v[166:169], v[62:65]
	v_mfma_f32_16x16x32_bf16 v[58:61], v[158:161], v[166:169], v[58:61]
	v_mfma_f32_16x16x32_bf16 v[54:57], v[150:153], v[174:177], v[54:57]
	v_mfma_f32_16x16x32_bf16 v[50:53], v[158:161], v[174:177], v[50:53]
	v_mfma_f32_16x16x32_bf16 v[46:49], v[150:153], v[182:185], v[46:49]
	v_mfma_f32_16x16x32_bf16 v[42:45], v[158:161], v[182:185], v[42:45]
	v_mfma_f32_16x16x32_bf16 v[38:41], v[150:153], v[192:195], v[38:41]
	v_mfma_f32_16x16x32_bf16 v[34:37], v[158:161], v[192:195], v[34:37]
	s_barrier
	s_add_u32 s0, s40, 0x84080
	s_addc_u32 s1, s41, 0
	s_add_i32 s10, s11, s31
	s_mov_b32 m0, s10
	s_nop 0
	global_load_lds_dwordx4 v132, s[0:1]
	s_add_i32 m0, s10, 0x2000
	s_nop 0
	global_load_lds_dwordx4 v136, s[0:1]
	s_waitcnt vmcnt(6)
	s_barrier
	v_mfma_f32_16x16x32_bf16 v[30:33], v[196:199], v[162:165], v[30:33]
	s_add_i32 s60, s60, 2
	s_add_u32 s15, s15, 0x100
	s_addc_u32 s59, s59, 0
	s_cmp_gt_u32 s60, 13
	s_mov_b64 s[20:21], s[34:35]
	v_mfma_f32_16x16x32_bf16 v[26:29], v[204:207], v[162:165], v[26:29]
	v_mfma_f32_16x16x32_bf16 v[22:25], v[196:199], v[170:173], v[22:25]
	v_mfma_f32_16x16x32_bf16 v[18:21], v[204:207], v[170:173], v[18:21]
	v_mfma_f32_16x16x32_bf16 v[14:17], v[196:199], v[178:181], v[14:17]
	v_mfma_f32_16x16x32_bf16 v[10:13], v[204:207], v[178:181], v[10:13]
	v_mfma_f32_16x16x32_bf16 v[6:9], v[196:199], v[186:189], v[6:9]
	v_mfma_f32_16x16x32_bf16 v[2:5], v[204:207], v[186:189], v[2:5]
	v_mfma_f32_16x16x32_bf16 v[30:33], v[200:203], v[166:169], v[30:33]
	v_mfma_f32_16x16x32_bf16 v[26:29], v[208:211], v[166:169], v[26:29]
	v_mfma_f32_16x16x32_bf16 v[22:25], v[200:203], v[174:177], v[22:25]
	v_mfma_f32_16x16x32_bf16 v[18:21], v[208:211], v[174:177], v[18:21]
	v_mfma_f32_16x16x32_bf16 v[14:17], v[200:203], v[182:185], v[14:17]
	v_mfma_f32_16x16x32_bf16 v[10:13], v[208:211], v[182:185], v[10:13]
	v_mfma_f32_16x16x32_bf16 v[6:9], v[200:203], v[192:195], v[6:9]
	v_mfma_f32_16x16x32_bf16 v[2:5], v[208:211], v[192:195], v[2:5]
	s_cbranch_scc1 .Lkdone_sc
	s_barrier
	s_branch .LBB0_987

; template <int MODE  , class Epi, class Sched>
; __device__ __forceinline__ void gemm_phase(LAS unsigned char* lds, const GemmDesc g, const Sched& S, const Epi& E) {
;     ...
;         const bool zero = E(acc, cur, wr, wc, fr, fq);
;         if (!has_next) break;
;         if (zero) {
; #pragma unroll
;             for (int a = 0; a < 2; ++a)
; #pragma unroll
;                 for (int b = 0; b < 2; ++b)
; #pragma unroll
;                     for (int m = 0; m < 4; ++m)
; #pragma unroll
;                         for (int n = 0; n < 2; ++n) acc[a][b][m][n] = (f32x4){0.f, 0.f, 0.f, 0.f};
;         }
.LBB0_990:
	s_mov_b64 s[20:21], -1
	s_and_b64 vcc, exec, s[18:19]
	s_cbranch_vccz .LBB0_975
	s_andn2_b64 vcc, exec, s[34:35]
	s_cbranch_vccnz .LBB0_974
	s_mov_b32 s100, 1
	s_branch .LBB0_974

; #define G_STAGE(bufoff, gbase, voff) do { _Pragma("unroll") for (int _i = 0; _i < 2; ++_i) \
;         __builtin_amdgcn_global_load_lds((const unsigned*)((const char*)(gbase) + (voff)[_i]), (LAS unsigned*)(lds + (bufoff) + ldsw + _i * 8192), 16, 0, 0); } while (0)
; #define G_WAIT_V(n) asm volatile("s_waitcnt vmcnt(" #n ")" ::: "memory")
; #define G_WAIT_L(n) asm volatile("s_waitcnt lgkmcnt(" #n ")" ::: "memory")
; #define G_BAR __builtin_amdgcn_s_barrier()
; #define G_SCHED __builtin_amdgcn_sched_barrier(0)
; template <int MODE  , class Epi, class Sched>
; __device__ __forceinline__ void gemm_phase(LAS unsigned char* lds, const GemmDesc g, const Sched& S, const Epi& E) {
;     ...
;     f32x4 acc[2][2][4][2];
; #pragma unroll
;     for (int a = 0; a < 2; ++a)
; #pragma unroll
;         for (int b = 0; b < 2; ++b)
; #pragma unroll
;             for (int m = 0; m < 4; ++m)
; #pragma unroll
;                 for (int n = 0; n < 2; ++n) acc[a][b][m][n] = (f32x4){0.f, 0.f, 0.f, 0.f};
;     ...
;             G_LDB(B0, 0, 0); G_SCHED; G_LDA(At, 0, 0); G_STAGE(G_SA(1, 1), a1 + hstepA, voffA);
;             G_WAIT_L(8); G_BAR; G_WAIT_L(0); G_MMA(0, 0, At, B0); G_BAR; G_SCHED;
;             G_LDB(B1, 0, 1); G_STAGE(G_SB(0, 0), b2, voffB);
;             G_BAR; G_WAIT_L(0); G_MMA(0, 1, At, B1); G_BAR;
;             G_LDA(At, 0, 1); G_STAGE(G_SA(0, 0), a2, voffA);
;             G_BAR; G_WAIT_L(0); G_MMA(1, 0, At, B0); G_BAR; G_SCHED;
;             G_STAGE(G_SB(0, 1), b2 + hstepB, voffB);
;             G_WAIT_V(6); G_BAR; G_MMA(1, 1, At, B1); G_BAR;
.LBB0_1016:
	s_add_u32 s85, s4, 0x100
	v_mov_b32_e32 v2, 0
	s_addc_u32 s86, s5, 0
	s_mov_b32 s87, -2
	s_mov_b32 s100, 1
	s_cmp_eq_u32 s101, 1
	s_cbranch_scc0 .Lnodb_s1a
	s_barrier
	s_mov_b32 s101, 0
.Lnodb_s1a:
	s_cmp_eq_u32 s100, 1
	s_cbranch_scc0 .LBB0_1017
	s_mov_b32 s100, 0
	ds_read_b128 v[130:133], v163
	ds_read_b128 v[134:137], v163 offset:1024
	ds_read_b128 v[154:157], v163 offset:2048
	ds_read_b128 v[170:173], v163 offset:3072
	s_add_u32 s4, s2, 0x100
	s_addc_u32 s5, s3, 0
	s_cmp_eq_u32 s87, 28
	s_cselect_b32 s53, s47, s5
	s_cselect_b32 s52, s46, s4
	s_cselect_b32 s51, s49, s86
	s_cselect_b32 s50, s48, s85
	s_add_u32 s98, s2, 0x84080
	s_addc_u32 s99, s3, 0
	s_add_i32 m0, s58, 0xc000
	ds_read_b128 v[174:177], v164
	ds_read_b128 v[178:181], v164 offset:1024
	ds_read_b128 v[182:185], v164 offset:2048
	ds_read_b128 v[186:189], v164 offset:3072
	ds_read_b128 v[192:195], v164 offset:4096
	ds_read_b128 v[196:199], v164 offset:5120
	ds_read_b128 v[200:203], v164 offset:6144
	ds_read_b128 v[204:207], v164 offset:7168
	global_load_lds_dwordx4 v138, s[98:99]
	s_add_i32 m0, s58, 0xe000
	s_nop 0
	global_load_lds_dwordx4 v142, s[98:99]
	s_waitcnt lgkmcnt(8)
	s_barrier
	s_waitcnt lgkmcnt(0)
	v_mfma_f32_16x16x32_bf16 v[126:129], v[130:133], v[174:177], 0
	v_mfma_f32_16x16x32_bf16 v[122:125], v[154:157], v[174:177], 0
	v_mfma_f32_16x16x32_bf16 v[110:113], v[130:133], v[182:185], 0
	v_mfma_f32_16x16x32_bf16 v[106:109], v[154:157], v[182:185], 0
	v_mfma_f32_16x16x32_bf16 v[94:97], v[130:133], v[192:195], 0
	v_mfma_f32_16x16x32_bf16 v[90:93], v[154:157], v[192:195], 0
	v_mfma_f32_16x16x32_bf16 v[78:81], v[130:133], v[200:203], 0
	v_mfma_f32_16x16x32_bf16 v[74:77], v[154:157], v[200:203], 0
	v_mfma_f32_16x16x32_bf16 v[126:129], v[134:137], v[178:181], v[126:129]
	v_mfma_f32_16x16x32_bf16 v[122:125], v[170:173], v[178:181], v[122:125]
	v_mfma_f32_16x16x32_bf16 v[110:113], v[134:137], v[186:189], v[110:113]
	v_mfma_f32_16x16x32_bf16 v[106:109], v[170:173], v[186:189], v[106:109]
	v_mfma_f32_16x16x32_bf16 v[94:97], v[134:137], v[196:199], v[94:97]
	v_mfma_f32_16x16x32_bf16 v[90:93], v[170:173], v[196:199], v[90:93]
	v_mfma_f32_16x16x32_bf16 v[78:81], v[134:137], v[204:207], v[78:81]
	v_mfma_f32_16x16x32_bf16 v[74:77], v[170:173], v[204:207], v[74:77]
	s_barrier
	s_add_i32 s0, s66, s57
	s_mov_b32 m0, s0
	ds_read_b128 v[208:211], v165
	ds_read_b128 v[212:215], v165 offset:1024
	ds_read_b128 v[216:219], v165 offset:2048
	ds_read_b128 v[220:223], v165 offset:3072
	global_load_lds_dwordx4 v140, s[50:51]
	s_add_i32 m0, s0, 0x2000
	s_nop 0
	global_load_lds_dwordx4 v144, s[50:51]
	s_barrier
	s_waitcnt lgkmcnt(0)
	v_mfma_f32_16x16x32_bf16 v[118:121], v[208:211], v[174:177], 0
	v_mfma_f32_16x16x32_bf16 v[114:117], v[216:219], v[174:177], 0
	v_mfma_f32_16x16x32_bf16 v[102:105], v[208:211], v[182:185], 0
	v_mfma_f32_16x16x32_bf16 v[98:101], v[216:219], v[182:185], 0
	v_mfma_f32_16x16x32_bf16 v[86:89], v[208:211], v[192:195], 0
	v_mfma_f32_16x16x32_bf16 v[82:85], v[216:219], v[192:195], 0
	v_mfma_f32_16x16x32_bf16 v[70:73], v[208:211], v[200:203], 0
	v_mfma_f32_16x16x32_bf16 v[66:69], v[216:219], v[200:203], 0
	v_mfma_f32_16x16x32_bf16 v[118:121], v[212:215], v[178:181], v[118:121]
	v_mfma_f32_16x16x32_bf16 v[114:117], v[220:223], v[178:181], v[114:117]
	v_mfma_f32_16x16x32_bf16 v[102:105], v[212:215], v[186:189], v[102:105]
	v_mfma_f32_16x16x32_bf16 v[98:101], v[220:223], v[186:189], v[98:101]
	v_mfma_f32_16x16x32_bf16 v[86:89], v[212:215], v[196:199], v[86:89]
	v_mfma_f32_16x16x32_bf16 v[82:85], v[220:223], v[196:199], v[82:85]
	v_mfma_f32_16x16x32_bf16 v[70:73], v[212:215], v[204:207], v[70:73]
	v_mfma_f32_16x16x32_bf16 v[66:69], v[220:223], v[204:207], v[66:69]
	s_mov_b32 m0, s58
	s_barrier
	ds_read_b128 v[174:177], v164 offset:16384
	ds_read_b128 v[178:181], v164 offset:17408
	ds_read_b128 v[182:185], v164 offset:18432
	ds_read_b128 v[186:189], v164 offset:19456
	ds_read_b128 v[192:195], v164 offset:20480
	ds_read_b128 v[196:199], v164 offset:21504
	ds_read_b128 v[200:203], v164 offset:22528
	ds_read_b128 v[204:207], v164 offset:23552
	global_load_lds_dwordx4 v138, s[52:53]
	s_mov_b32 m0, s59
	s_nop 0
	global_load_lds_dwordx4 v142, s[52:53]
	s_barrier
	s_waitcnt lgkmcnt(0)
	v_mfma_f32_16x16x32_bf16 v[62:65], v[130:133], v[174:177], 0
	v_mfma_f32_16x16x32_bf16 v[58:61], v[154:157], v[174:177], 0
	v_mfma_f32_16x16x32_bf16 v[46:49], v[130:133], v[182:185], 0
	v_mfma_f32_16x16x32_bf16 v[42:45], v[154:157], v[182:185], 0
	v_mfma_f32_16x16x32_bf16 v[30:33], v[130:133], v[192:195], 0
	v_mfma_f32_16x16x32_bf16 v[26:29], v[154:157], v[192:195], 0
	v_mfma_f32_16x16x32_bf16 v[14:17], v[130:133], v[200:203], 0
	v_mfma_f32_16x16x32_bf16 v[10:13], v[154:157], v[200:203], 0
	v_mfma_f32_16x16x32_bf16 v[62:65], v[134:137], v[178:181], v[62:65]
	v_mfma_f32_16x16x32_bf16 v[58:61], v[170:173], v[178:181], v[58:61]
	v_mfma_f32_16x16x32_bf16 v[46:49], v[134:137], v[186:189], v[46:49]
	v_mfma_f32_16x16x32_bf16 v[42:45], v[170:173], v[186:189], v[42:45]
	v_mfma_f32_16x16x32_bf16 v[30:33], v[134:137], v[196:199], v[30:33]
	v_mfma_f32_16x16x32_bf16 v[26:29], v[170:173], v[196:199], v[26:29]
	v_mfma_f32_16x16x32_bf16 v[14:17], v[134:137], v[204:207], v[14:17]
	v_mfma_f32_16x16x32_bf16 v[10:13], v[170:173], v[204:207], v[10:13]
	s_barrier
	s_add_u32 s0, s50, 0x84000
	s_addc_u32 s1, s51, 0
	s_add_i32 s2, s67, s57
	s_mov_b32 m0, s2
	s_nop 0
	global_load_lds_dwordx4 v140, s[0:1]
	s_add_i32 m0, s2, 0x2000
	s_nop 0
	global_load_lds_dwordx4 v144, s[0:1]
	s_waitcnt vmcnt(6)
	s_barrier
; #define G_STAGE(bufoff, gbase, voff) do { _Pragma("unroll") for (int _i = 0; _i < 2; ++_i) \
;         __builtin_amdgcn_global_load_lds((const unsigned*)((const char*)(gbase) + (voff)[_i]), (LAS unsigned*)(lds + (bufoff) + ldsw + _i * 8192), 16, 0, 0); } while (0)
; #define G_WAIT_V(n) asm volatile("s_waitcnt vmcnt(" #n ")" ::: "memory")
; #define G_WAIT_L(n) asm volatile("s_waitcnt lgkmcnt(" #n ")" ::: "memory")
; #define G_BAR __builtin_amdgcn_s_barrier()
; #define G_SCHED __builtin_amdgcn_sched_barrier(0)
; template <int MODE  , class Epi, class Sched>
; __device__ __forceinline__ void gemm_phase(LAS unsigned char* lds, const GemmDesc g, const Sched& S, const Epi& E) {
;     ...
;             G_WAIT_V(6); G_BAR; G_MMA(1, 1, At, B1); G_BAR;
;             G_LDB(B0, 1, 0); G_SCHED; G_LDA(At, 1, 0); G_STAGE(G_SA(0, 1), a2 + hstepA, voffA);
;             G_WAIT_L(8); G_BAR; G_WAIT_L(0); G_MMA(0, 0, At, B0); G_BAR; G_SCHED;
;             G_LDB(B1, 1, 1); G_STAGE(G_SB(1, 0), b3, voffB);
	v_mfma_f32_16x16x32_bf16 v[54:57], v[208:211], v[174:177], 0
	v_mfma_f32_16x16x32_bf16 v[50:53], v[216:219], v[174:177], 0
	v_mfma_f32_16x16x32_bf16 v[38:41], v[208:211], v[182:185], 0
	v_mfma_f32_16x16x32_bf16 v[34:37], v[216:219], v[182:185], 0
	v_mfma_f32_16x16x32_bf16 v[22:25], v[208:211], v[192:195], 0
	v_mfma_f32_16x16x32_bf16 v[18:21], v[216:219], v[192:195], 0
	v_mfma_f32_16x16x32_bf16 v[6:9], v[208:211], v[200:203], 0
	v_mfma_f32_16x16x32_bf16 v[2:5], v[216:219], v[200:203], 0
	v_mfma_f32_16x16x32_bf16 v[54:57], v[212:215], v[178:181], v[54:57]
	v_mfma_f32_16x16x32_bf16 v[50:53], v[220:223], v[178:181], v[50:53]
	v_mfma_f32_16x16x32_bf16 v[38:41], v[212:215], v[186:189], v[38:41]
	v_mfma_f32_16x16x32_bf16 v[34:37], v[220:223], v[186:189], v[34:37]
	v_mfma_f32_16x16x32_bf16 v[22:25], v[212:215], v[196:199], v[22:25]
	v_mfma_f32_16x16x32_bf16 v[18:21], v[220:223], v[196:199], v[18:21]
	v_mfma_f32_16x16x32_bf16 v[6:9], v[212:215], v[204:207], v[6:9]
	v_mfma_f32_16x16x32_bf16 v[2:5], v[220:223], v[204:207], v[2:5]
	s_add_i32 s2, 0, 0x18000
	v_add_u32_e32 v146, s2, v160
	s_barrier
	ds_read_b128 v[130:133], v146
	ds_read_b128 v[134:137], v146 offset:1024
	ds_read_b128 v[154:157], v146 offset:2048
	ds_read_b128 v[170:173], v146 offset:3072
	s_add_u32 s0, s52, 0x84000
	s_addc_u32 s1, s53, 0
	s_mov_b32 m0, s60
	ds_read_b128 v[174:177], v164 offset:32768
	ds_read_b128 v[178:181], v164 offset:33792
	ds_read_b128 v[182:185], v164 offset:34816
	ds_read_b128 v[186:189], v164 offset:35840
	ds_read_b128 v[192:195], v164 offset:36864
	ds_read_b128 v[196:199], v164 offset:37888
	ds_read_b128 v[200:203], v164 offset:38912
	ds_read_b128 v[204:207], v164 offset:39936
	global_load_lds_dwordx4 v138, s[0:1]
	s_mov_b32 m0, s61
	s_nop 0
	global_load_lds_dwordx4 v142, s[0:1]
	s_waitcnt lgkmcnt(8)
	s_barrier
	s_waitcnt lgkmcnt(0)
	v_mfma_f32_16x16x32_bf16 v[126:129], v[130:133], v[174:177], v[126:129]
	v_mfma_f32_16x16x32_bf16 v[122:125], v[154:157], v[174:177], v[122:125]
	v_mfma_f32_16x16x32_bf16 v[110:113], v[130:133], v[182:185], v[110:113]
	v_mfma_f32_16x16x32_bf16 v[106:109], v[154:157], v[182:185], v[106:109]
	v_mfma_f32_16x16x32_bf16 v[94:97], v[130:133], v[192:195], v[94:97]
	v_mfma_f32_16x16x32_bf16 v[90:93], v[154:157], v[192:195], v[90:93]
	v_mfma_f32_16x16x32_bf16 v[78:81], v[130:133], v[200:203], v[78:81]
	v_mfma_f32_16x16x32_bf16 v[74:77], v[154:157], v[200:203], v[74:77]
	v_mfma_f32_16x16x32_bf16 v[126:129], v[134:137], v[178:181], v[126:129]
	v_mfma_f32_16x16x32_bf16 v[122:125], v[170:173], v[178:181], v[122:125]
	v_mfma_f32_16x16x32_bf16 v[110:113], v[134:137], v[186:189], v[110:113]
	v_mfma_f32_16x16x32_bf16 v[106:109], v[170:173], v[186:189], v[106:109]
	v_mfma_f32_16x16x32_bf16 v[94:97], v[134:137], v[196:199], v[94:97]
	v_mfma_f32_16x16x32_bf16 v[90:93], v[170:173], v[196:199], v[90:93]
	v_mfma_f32_16x16x32_bf16 v[78:81], v[134:137], v[204:207], v[78:81]
	v_mfma_f32_16x16x32_bf16 v[74:77], v[170:173], v[204:207], v[74:77]
	s_barrier
	s_add_i32 s3, 0, 0x1c000
	s_add_i32 s0, s2, s57
	v_add_u32_e32 v146, s3, v160
	s_add_u32 s98, s50, 0x80
	s_addc_u32 s99, s51, 0
	s_mov_b32 m0, s0
	ds_read_b128 v[208:211], v146
	ds_read_b128 v[212:215], v146 offset:1024
	ds_read_b128 v[216:219], v146 offset:2048
	ds_read_b128 v[220:223], v146 offset:3072
	global_load_lds_dwordx4 v140, s[98:99]
	s_add_i32 m0, s0, 0x2000
	s_nop 0
	global_load_lds_dwordx4 v144, s[98:99]
	s_barrier
; #define G_STAGE(bufoff, gbase, voff) do { _Pragma("unroll") for (int _i = 0; _i < 2; ++_i) \
;         __builtin_amdgcn_global_load_lds((const unsigned*)((const char*)(gbase) + (voff)[_i]), (LAS unsigned*)(lds + (bufoff) + ldsw + _i * 8192), 16, 0, 0); } while (0)
; #define G_WAIT_V(n) asm volatile("s_waitcnt vmcnt(" #n ")" ::: "memory")
; #define G_WAIT_L(n) asm volatile("s_waitcnt lgkmcnt(" #n ")" ::: "memory")
; #define G_BAR __builtin_amdgcn_s_barrier()
; #define G_SCHED __builtin_amdgcn_sched_barrier(0)
; template <int MODE  , class Epi, class Sched>
; __device__ __forceinline__ void gemm_phase(LAS unsigned char* lds, const GemmDesc g, const Sched& S, const Epi& E) {
;     ...
;             G_BAR; G_WAIT_L(0); G_MMA(0, 1, At, B1); G_BAR;
;             G_LDA(At, 1, 1); G_STAGE(G_SA(1, 0), a3, voffA);
;             G_BAR; G_WAIT_L(0); G_MMA(1, 0, At, B0); G_BAR; G_SCHED;
;             G_STAGE(G_SB(1, 1), b3 + hstepB, voffB);
;             G_WAIT_V(6); G_BAR; G_MMA(1, 1, At, B1); G_BAR;
	s_waitcnt lgkmcnt(0)
	v_mfma_f32_16x16x32_bf16 v[118:121], v[208:211], v[174:177], v[118:121]
	v_mfma_f32_16x16x32_bf16 v[114:117], v[216:219], v[174:177], v[114:117]
	v_mfma_f32_16x16x32_bf16 v[102:105], v[208:211], v[182:185], v[102:105]
	v_mfma_f32_16x16x32_bf16 v[98:101], v[216:219], v[182:185], v[98:101]
	v_mfma_f32_16x16x32_bf16 v[86:89], v[208:211], v[192:195], v[86:89]
	v_mfma_f32_16x16x32_bf16 v[82:85], v[216:219], v[192:195], v[82:85]
	v_mfma_f32_16x16x32_bf16 v[70:73], v[208:211], v[200:203], v[70:73]
	v_mfma_f32_16x16x32_bf16 v[66:69], v[216:219], v[200:203], v[66:69]
	v_mfma_f32_16x16x32_bf16 v[118:121], v[212:215], v[178:181], v[118:121]
	v_mfma_f32_16x16x32_bf16 v[114:117], v[220:223], v[178:181], v[114:117]
	v_mfma_f32_16x16x32_bf16 v[102:105], v[212:215], v[186:189], v[102:105]
	v_mfma_f32_16x16x32_bf16 v[98:101], v[220:223], v[186:189], v[98:101]
	v_mfma_f32_16x16x32_bf16 v[86:89], v[212:215], v[196:199], v[86:89]
	v_mfma_f32_16x16x32_bf16 v[82:85], v[220:223], v[196:199], v[82:85]
	v_mfma_f32_16x16x32_bf16 v[70:73], v[212:215], v[204:207], v[70:73]
	v_mfma_f32_16x16x32_bf16 v[66:69], v[220:223], v[204:207], v[66:69]
	s_mov_b32 m0, s64
	s_add_u32 s98, s52, 0x80
	s_addc_u32 s99, s53, 0
	s_barrier
	ds_read_b128 v[174:177], v164 offset:49152
	ds_read_b128 v[178:181], v164 offset:50176
	ds_read_b128 v[182:185], v164 offset:51200
	ds_read_b128 v[186:189], v164 offset:52224
	ds_read_b128 v[192:195], v164 offset:53248
	ds_read_b128 v[196:199], v164 offset:54272
	ds_read_b128 v[200:203], v164 offset:55296
	ds_read_b128 v[204:207], v164 offset:56320
	global_load_lds_dwordx4 v138, s[98:99]
	s_mov_b32 m0, s65
	s_nop 0
	global_load_lds_dwordx4 v142, s[98:99]
	s_barrier
	s_waitcnt lgkmcnt(0)
	v_mfma_f32_16x16x32_bf16 v[62:65], v[130:133], v[174:177], v[62:65]
	v_mfma_f32_16x16x32_bf16 v[58:61], v[154:157], v[174:177], v[58:61]
	v_mfma_f32_16x16x32_bf16 v[46:49], v[130:133], v[182:185], v[46:49]
	v_mfma_f32_16x16x32_bf16 v[42:45], v[154:157], v[182:185], v[42:45]
	v_mfma_f32_16x16x32_bf16 v[30:33], v[130:133], v[192:195], v[30:33]
	v_mfma_f32_16x16x32_bf16 v[26:29], v[154:157], v[192:195], v[26:29]
	v_mfma_f32_16x16x32_bf16 v[14:17], v[130:133], v[200:203], v[14:17]
	v_mfma_f32_16x16x32_bf16 v[10:13], v[154:157], v[200:203], v[10:13]
	v_mfma_f32_16x16x32_bf16 v[62:65], v[134:137], v[178:181], v[62:65]
	v_mfma_f32_16x16x32_bf16 v[58:61], v[170:173], v[178:181], v[58:61]
	v_mfma_f32_16x16x32_bf16 v[46:49], v[134:137], v[186:189], v[46:49]
	v_mfma_f32_16x16x32_bf16 v[42:45], v[170:173], v[186:189], v[42:45]
	v_mfma_f32_16x16x32_bf16 v[30:33], v[134:137], v[196:199], v[30:33]
	v_mfma_f32_16x16x32_bf16 v[26:29], v[170:173], v[196:199], v[26:29]
	v_mfma_f32_16x16x32_bf16 v[14:17], v[134:137], v[204:207], v[14:17]
	v_mfma_f32_16x16x32_bf16 v[10:13], v[170:173], v[204:207], v[10:13]
	s_barrier
	s_add_u32 s0, s50, 0x84080
	s_addc_u32 s1, s51, 0
	s_add_i32 s2, s3, s57
	s_mov_b32 m0, s2
	s_nop 0
	global_load_lds_dwordx4 v140, s[0:1]
	s_add_i32 m0, s2, 0x2000
	s_nop 0
	global_load_lds_dwordx4 v144, s[0:1]
	s_waitcnt vmcnt(6)
	s_barrier
	v_mfma_f32_16x16x32_bf16 v[54:57], v[208:211], v[174:177], v[54:57]
	s_add_i32 s87, s87, 2
	s_add_u32 s85, s85, 0x100
	s_addc_u32 s86, s86, 0
	s_cmp_gt_u32 s87, 29
	s_mov_b64 s[2:3], s[4:5]
	v_mfma_f32_16x16x32_bf16 v[50:53], v[216:219], v[174:177], v[50:53]
	v_mfma_f32_16x16x32_bf16 v[38:41], v[208:211], v[182:185], v[38:41]
	v_mfma_f32_16x16x32_bf16 v[34:37], v[216:219], v[182:185], v[34:37]
	v_mfma_f32_16x16x32_bf16 v[22:25], v[208:211], v[192:195], v[22:25]
	v_mfma_f32_16x16x32_bf16 v[18:21], v[216:219], v[192:195], v[18:21]
	v_mfma_f32_16x16x32_bf16 v[6:9], v[208:211], v[200:203], v[6:9]
	v_mfma_f32_16x16x32_bf16 v[2:5], v[216:219], v[200:203], v[2:5]
	v_mfma_f32_16x16x32_bf16 v[54:57], v[212:215], v[178:181], v[54:57]
	v_mfma_f32_16x16x32_bf16 v[50:53], v[220:223], v[178:181], v[50:53]
	v_mfma_f32_16x16x32_bf16 v[38:41], v[212:215], v[186:189], v[38:41]
	v_mfma_f32_16x16x32_bf16 v[34:37], v[220:223], v[186:189], v[34:37]
	v_mfma_f32_16x16x32_bf16 v[22:25], v[212:215], v[196:199], v[22:25]
	v_mfma_f32_16x16x32_bf16 v[18:21], v[220:223], v[196:199], v[18:21]
	v_mfma_f32_16x16x32_bf16 v[6:9], v[212:215], v[204:207], v[6:9]
	v_mfma_f32_16x16x32_bf16 v[2:5], v[220:223], v[204:207], v[2:5]
	s_cbranch_scc1 .Lkdone_s1a
	s_barrier
	s_branch .LBB0_1017
